# LN epilogue de-serialised: second residual batch issued before waiting for the first (7 fused-LayerNorm GEMM sites), on top of mask+wait edits
# baseline (speedup 1.0000x reference)
.LBB0_1285:
	v_mov_b32_e32 v186, v177
	s_mov_b32 s8, s3
	v_mov_b32_e32 v187, v178
	s_mov_b32 s9, s72
	s_lshl_b32 s7, s14, 2
	s_ashr_i32 s10, s9, 1
	s_lshl_b32 s31, s8, 6
	s_add_i32 s38, s10, s7
	s_lshl_b32 s10, s40, 8
	s_lshl_b32 s6, s9, 5
	s_ashr_i32 s39, s38, 31
	s_add_i32 s79, s31, s10
	v_add_u32_e32 v128, s79, v186
	s_and_b32 s7, s6, 32
	s_lshl_b64 s[38:39], s[38:39], 22
	v_ashrrev_i32_e32 v129, 31, v128
	s_add_u32 s38, s58, s38
	v_lshlrev_b64 v[128:129], 7, v[128:129]
	s_addc_u32 s39, s59, s39
	v_lshlrev_b32_e32 v144, 3, v187
	v_lshl_add_u64 v[128:129], s[38:39], 0, v[128:129]
	s_lshl_b32 s12, s7, 1
	v_ashrrev_i32_e32 v145, 31, v144
	v_lshl_add_u64 v[128:129], v[128:129], 0, s[12:13]
	v_lshl_add_u64 v[132:133], v[144:145], 1, v[128:129]
	v_add_co_u32_e32 v128, vcc, s74, v132
	global_load_dwordx4 v[134:137], v[132:133], off
	global_load_dwordx4 v[138:141], v[132:133], off offset:2048
	v_addc_co_u32_e32 v129, vcc, 0, v133, vcc
	v_add_co_u32_e32 v130, vcc, s51, v132
	global_load_dwordx4 v[146:149], v[128:129], off offset:-4096
	s_nop 0
	v_addc_co_u32_e32 v131, vcc, 0, v133, vcc
	global_load_dwordx4 v[150:153], v[130:131], off offset:2048
	v_add_co_u32_e32 v130, vcc, s73, v132
	s_lshl_b32 s7, s14, 8
	s_nop 0
	v_addc_co_u32_e32 v131, vcc, 0, v133, vcc
	global_load_dwordx4 v[154:157], v[130:131], off
	global_load_dwordx4 v[188:191], v[128:129], off
	global_load_dwordx4 v[192:195], v[130:131], off offset:2048
	s_nop 0
	global_load_dwordx4 v[128:131], v[128:129], off offset:2048
	s_add_i32 s6, s6, s7
	s_mov_b32 s101, 0
	s_mov_b32 s100, s78
	v_lshl_add_u64 v[246:247], v[132:133], 0, s[100:101]
	s_mov_b32 s100, s88
	v_lshl_add_u64 v[252:253], v[132:133], 0, s[100:101]
	s_mov_b32 s100, s55
	v_lshl_add_u64 v[230:231], v[132:133], 0, s[100:101]
	s_mov_b32 s100, s75
	v_lshl_add_u64 v[234:235], v[132:133], 0, s[100:101]
	global_load_dwordx4 v[222:225], v[246:247], off offset:-4096
	global_load_dwordx4 v[226:229], v[252:253], off offset:-4096
	global_load_dwordx4 v[230:233], v[230:231], off offset:2048
	global_load_dwordx4 v[234:237], v[234:235], off offset:2048
	global_load_dwordx4 v[238:241], v[246:247], off
	global_load_dwordx4 v[242:245], v[252:253], off
	global_load_dwordx4 v[246:249], v[246:247], off offset:2048
	global_load_dwordx4 v[252:255], v[252:253], off offset:2048
	s_waitcnt vmcnt(8)
	v_lshlrev_b32_e32 v142, 16, v134
	v_and_b32_e32 v143, 0xffff0000, v134
	v_lshlrev_b32_e32 v134, 16, v135
	v_and_b32_e32 v135, 0xffff0000, v135
	v_lshlrev_b32_e32 v158, 16, v136
	v_and_b32_e32 v159, 0xffff0000, v136
	v_lshlrev_b32_e32 v136, 16, v137
	v_and_b32_e32 v137, 0xffff0000, v137
	v_lshlrev_b32_e32 v174, 16, v138
	v_and_b32_e32 v175, 0xffff0000, v138
	v_lshlrev_b32_e32 v138, 16, v139
	v_and_b32_e32 v139, 0xffff0000, v139
	v_lshlrev_b32_e32 v196, 16, v140
	v_and_b32_e32 v197, 0xffff0000, v140
	v_lshlrev_b32_e32 v140, 16, v141
	v_and_b32_e32 v141, 0xffff0000, v141
	v_pk_fma_f32 v[102:103], v[134:135], s[28:29], v[102:103] op_sel_hi:[1,0,1]
	v_pk_fma_f32 v[90:91], v[136:137], s[28:29], v[90:91] op_sel_hi:[1,0,1]
	v_lshlrev_b32_e32 v134, 16, v146
	v_and_b32_e32 v135, 0xffff0000, v146
	v_lshlrev_b32_e32 v136, 16, v147
	v_and_b32_e32 v137, 0xffff0000, v147
	v_pk_fma_f32 v[86:87], v[138:139], s[28:29], v[86:87] op_sel_hi:[1,0,1]
	v_pk_fma_f32 v[82:83], v[140:141], s[28:29], v[82:83] op_sel_hi:[1,0,1]
	v_lshlrev_b32_e32 v138, 16, v150
	v_and_b32_e32 v139, 0xffff0000, v150
	v_lshlrev_b32_e32 v140, 16, v151
	v_and_b32_e32 v141, 0xffff0000, v151
	v_pk_fma_f32 v[30:31], v[136:137], s[28:29], v[30:31] op_sel_hi:[1,0,1]
	v_pk_fma_f32 v[28:29], v[134:135], s[28:29], v[28:29] op_sel_hi:[1,0,1]
	v_lshlrev_b32_e32 v134, 16, v154
	v_and_b32_e32 v135, 0xffff0000, v154
	v_lshlrev_b32_e32 v136, 16, v155
	v_and_b32_e32 v137, 0xffff0000, v155
	v_pk_fma_f32 v[100:101], v[142:143], s[28:29], v[100:101] op_sel_hi:[1,0,1]
	v_lshlrev_b32_e32 v142, 16, v148
	v_and_b32_e32 v143, 0xffff0000, v148
	v_pk_fma_f32 v[6:7], v[140:141], s[28:29], v[6:7] op_sel_hi:[1,0,1]
	v_pk_fma_f32 v[4:5], v[138:139], s[28:29], v[4:5] op_sel_hi:[1,0,1]
	v_lshlrev_b32_e32 v138, 16, v156
	v_and_b32_e32 v139, 0xffff0000, v156
	v_lshlrev_b32_e32 v140, 16, v157
	v_and_b32_e32 v141, 0xffff0000, v157
	v_pk_fma_f32 v[98:99], v[136:137], s[28:29], v[98:99] op_sel_hi:[1,0,1]
	v_pk_fma_f32 v[96:97], v[134:135], s[28:29], v[96:97] op_sel_hi:[1,0,1]
	v_lshlrev_b32_e32 v134, 16, v188
	v_and_b32_e32 v135, 0xffff0000, v188
	v_lshlrev_b32_e32 v136, 16, v189
	v_and_b32_e32 v137, 0xffff0000, v189
	v_pk_fma_f32 v[16:17], v[142:143], s[28:29], v[16:17] op_sel_hi:[1,0,1]
	v_pk_fma_f32 v[94:95], v[140:141], s[28:29], v[94:95] op_sel_hi:[1,0,1]
	v_pk_fma_f32 v[92:93], v[138:139], s[28:29], v[92:93] op_sel_hi:[1,0,1]
	v_lshlrev_b32_e32 v138, 16, v190
	v_and_b32_e32 v139, 0xffff0000, v190
	v_lshlrev_b32_e32 v140, 16, v191
	v_and_b32_e32 v141, 0xffff0000, v191
	v_pk_fma_f32 v[14:15], v[136:137], s[28:29], v[14:15] op_sel_hi:[1,0,1]
	v_pk_fma_f32 v[12:13], v[134:135], s[28:29], v[12:13] op_sel_hi:[1,0,1]
	v_lshlrev_b32_e32 v134, 16, v192
	v_and_b32_e32 v135, 0xffff0000, v192
	v_lshlrev_b32_e32 v136, 16, v193
	v_and_b32_e32 v137, 0xffff0000, v193
	v_add_co_u32_e32 v142, vcc, s78, v132
	v_lshlrev_b32_e32 v146, 16, v149
	v_and_b32_e32 v147, 0xffff0000, v149
	v_lshlrev_b32_e32 v148, 16, v152
	v_and_b32_e32 v149, 0xffff0000, v152
	v_lshlrev_b32_e32 v150, 16, v153
	v_and_b32_e32 v151, 0xffff0000, v153
	v_pk_fma_f32 v[10:11], v[140:141], s[28:29], v[10:11] op_sel_hi:[1,0,1]
	v_pk_fma_f32 v[8:9], v[138:139], s[28:29], v[8:9] op_sel_hi:[1,0,1]
	v_lshlrev_b32_e32 v138, 16, v194
	v_and_b32_e32 v139, 0xffff0000, v194
	v_lshlrev_b32_e32 v140, 16, v195
	v_and_b32_e32 v141, 0xffff0000, v195
	v_pk_fma_f32 v[110:111], v[136:137], s[28:29], v[110:111] op_sel_hi:[1,0,1]
	v_pk_fma_f32 v[108:109], v[134:135], s[28:29], v[108:109] op_sel_hi:[1,0,1]
	v_lshlrev_b32_e32 v134, 16, v128
	v_and_b32_e32 v135, 0xffff0000, v128
	v_lshlrev_b32_e32 v128, 16, v129
	v_and_b32_e32 v129, 0xffff0000, v129
	v_lshlrev_b32_e32 v136, 16, v130
	v_and_b32_e32 v137, 0xffff0000, v130
	v_lshlrev_b32_e32 v130, 16, v131
	v_and_b32_e32 v131, 0xffff0000, v131
	v_addc_co_u32_e32 v143, vcc, 0, v133, vcc
	v_pk_fma_f32 v[88:89], v[158:159], s[28:29], v[88:89] op_sel_hi:[1,0,1]
	v_pk_fma_f32 v[84:85], v[174:175], s[28:29], v[84:85] op_sel_hi:[1,0,1]
	v_pk_fma_f32 v[80:81], v[196:197], s[28:29], v[80:81] op_sel_hi:[1,0,1]
	v_pk_fma_f32 v[18:19], v[146:147], s[28:29], v[18:19] op_sel_hi:[1,0,1]
	v_pk_fma_f32 v[2:3], v[150:151], s[28:29], v[2:3] op_sel_hi:[1,0,1]
	v_pk_fma_f32 v[0:1], v[148:149], s[28:29], v[0:1] op_sel_hi:[1,0,1]
	v_pk_fma_f32 v[106:107], v[140:141], s[28:29], v[106:107] op_sel_hi:[1,0,1]
	v_pk_fma_f32 v[104:105], v[138:139], s[28:29], v[104:105] op_sel_hi:[1,0,1]
	v_pk_fma_f32 v[26:27], v[128:129], s[28:29], v[26:27] op_sel_hi:[1,0,1]
	v_pk_fma_f32 v[24:25], v[134:135], s[28:29], v[24:25] op_sel_hi:[1,0,1]
	v_pk_fma_f32 v[22:23], v[130:131], s[28:29], v[22:23] op_sel_hi:[1,0,1]
	v_pk_fma_f32 v[20:21], v[136:137], s[28:29], v[20:21] op_sel_hi:[1,0,1]
	v_add_co_u32_e32 v158, vcc, s88, v132
	s_nop 1
	v_addc_co_u32_e32 v159, vcc, 0, v133, vcc
	v_add_co_u32_e32 v138, vcc, s55, v132
	s_nop 0
	v_addc_co_u32_e32 v139, vcc, 0, v133, vcc
	v_add_co_u32_e32 v132, vcc, s75, v132
	v_pk_add_f32 v[174:175], v[102:103], v[90:91]
	s_nop 0
	v_addc_co_u32_e32 v133, vcc, 0, v133, vcc
	v_cmp_eq_u32_e32 vcc, 0, v187
	s_waitcnt vmcnt(7)
	v_lshlrev_b32_e32 v132, 16, v222
	v_and_b32_e32 v133, 0xffff0000, v222
	v_lshlrev_b32_e32 v128, 16, v223
	v_and_b32_e32 v129, 0xffff0000, v223
	v_pk_fma_f32 v[118:119], v[128:129], s[28:29], v[118:119] op_sel_hi:[1,0,1]
	s_waitcnt vmcnt(6)
	v_lshlrev_b32_e32 v128, 16, v226
	v_and_b32_e32 v129, 0xffff0000, v226
	v_lshlrev_b32_e32 v142, 16, v224
	v_and_b32_e32 v143, 0xffff0000, v224
	v_lshlrev_b32_e32 v130, 16, v225
	v_and_b32_e32 v131, 0xffff0000, v225
	v_pk_fma_f32 v[116:117], v[132:133], s[28:29], v[116:117] op_sel_hi:[1,0,1]
	v_lshlrev_b32_e32 v132, 16, v228
	v_and_b32_e32 v133, 0xffff0000, v228
	v_pk_fma_f32 v[36:37], v[128:129], s[28:29], v[36:37] op_sel_hi:[1,0,1]
	s_waitcnt vmcnt(5)
	v_lshlrev_b32_e32 v128, 16, v230
	v_and_b32_e32 v129, 0xffff0000, v230
	v_pk_fma_f32 v[114:115], v[130:131], s[28:29], v[114:115] op_sel_hi:[1,0,1]
	v_lshlrev_b32_e32 v130, 16, v227
	v_and_b32_e32 v131, 0xffff0000, v227
	v_pk_fma_f32 v[32:33], v[132:133], s[28:29], v[32:33] op_sel_hi:[1,0,1]
	v_lshlrev_b32_e32 v132, 16, v232
	v_and_b32_e32 v133, 0xffff0000, v232
	v_pk_fma_f32 v[124:125], v[128:129], s[28:29], v[124:125] op_sel_hi:[1,0,1]
	s_waitcnt vmcnt(4)
	v_lshlrev_b32_e32 v128, 16, v234
	v_and_b32_e32 v129, 0xffff0000, v234
	v_lshlrev_b32_e32 v134, 16, v229
	v_and_b32_e32 v135, 0xffff0000, v229
	v_pk_fma_f32 v[38:39], v[130:131], s[28:29], v[38:39] op_sel_hi:[1,0,1]
	v_lshlrev_b32_e32 v130, 16, v231
	v_and_b32_e32 v131, 0xffff0000, v231
	v_pk_fma_f32 v[120:121], v[132:133], s[28:29], v[120:121] op_sel_hi:[1,0,1]
	v_lshlrev_b32_e32 v132, 16, v236
	v_and_b32_e32 v133, 0xffff0000, v236
	v_pk_fma_f32 v[44:45], v[128:129], s[28:29], v[44:45] op_sel_hi:[1,0,1]
	s_waitcnt vmcnt(3)
	v_lshlrev_b32_e32 v128, 16, v238
	v_and_b32_e32 v129, 0xffff0000, v238
	v_pk_fma_f32 v[34:35], v[134:135], s[28:29], v[34:35] op_sel_hi:[1,0,1]
	v_lshlrev_b32_e32 v134, 16, v233
	v_and_b32_e32 v135, 0xffff0000, v233
	v_pk_fma_f32 v[126:127], v[130:131], s[28:29], v[126:127] op_sel_hi:[1,0,1]
	v_lshlrev_b32_e32 v130, 16, v235
	v_and_b32_e32 v131, 0xffff0000, v235
	v_pk_fma_f32 v[40:41], v[132:133], s[28:29], v[40:41] op_sel_hi:[1,0,1]
	v_pk_fma_f32 v[132:133], v[128:129], s[28:29], v[76:77] op_sel_hi:[1,0,1]
	s_waitcnt vmcnt(2)
	v_lshlrev_b32_e32 v76, 16, v244
	v_and_b32_e32 v77, 0xffff0000, v244
	v_pk_fma_f32 v[122:123], v[134:135], s[28:29], v[122:123] op_sel_hi:[1,0,1]
	v_lshlrev_b32_e32 v134, 16, v237
	v_and_b32_e32 v135, 0xffff0000, v237
	v_pk_fma_f32 v[46:47], v[130:131], s[28:29], v[46:47] op_sel_hi:[1,0,1]
	v_lshlrev_b32_e32 v130, 16, v239
	v_and_b32_e32 v131, 0xffff0000, v239
	v_lshlrev_b32_e32 v136, 16, v240
	v_and_b32_e32 v137, 0xffff0000, v240
	v_lshlrev_b32_e32 v138, 16, v241
	v_and_b32_e32 v139, 0xffff0000, v241
	v_pk_fma_f32 v[48:49], v[76:77], s[28:29], v[48:49] op_sel_hi:[1,0,1]
	s_waitcnt vmcnt(1)
	v_lshlrev_b32_e32 v76, 16, v248
	v_and_b32_e32 v77, 0xffff0000, v248
	v_pk_fma_f32 v[42:43], v[134:135], s[28:29], v[42:43] op_sel_hi:[1,0,1]
	v_pk_fma_f32 v[134:135], v[130:131], s[28:29], v[78:79] op_sel_hi:[1,0,1]
	v_pk_fma_f32 v[130:131], v[138:139], s[28:29], v[74:75] op_sel_hi:[1,0,1]
	v_pk_fma_f32 v[128:129], v[136:137], s[28:29], v[72:73] op_sel_hi:[1,0,1]
	v_lshlrev_b32_e32 v72, 16, v242
	v_and_b32_e32 v73, 0xffff0000, v242
	v_lshlrev_b32_e32 v74, 16, v243
	v_and_b32_e32 v75, 0xffff0000, v243
	v_lshlrev_b32_e32 v78, 16, v245
	v_and_b32_e32 v79, 0xffff0000, v245
	v_pk_fma_f32 v[136:137], v[76:77], s[28:29], v[64:65] op_sel_hi:[1,0,1]
	s_waitcnt vmcnt(0)
	v_lshlrev_b32_e32 v64, 16, v252
	v_and_b32_e32 v65, 0xffff0000, v252
	v_pk_fma_f32 v[54:55], v[74:75], s[28:29], v[54:55] op_sel_hi:[1,0,1]
	v_pk_fma_f32 v[52:53], v[72:73], s[28:29], v[52:53] op_sel_hi:[1,0,1]
	v_pk_fma_f32 v[50:51], v[78:79], s[28:29], v[50:51] op_sel_hi:[1,0,1]
	v_lshlrev_b32_e32 v72, 16, v246
	v_and_b32_e32 v73, 0xffff0000, v246
	v_lshlrev_b32_e32 v74, 16, v247
	v_and_b32_e32 v75, 0xffff0000, v247
	v_lshlrev_b32_e32 v78, 16, v249
	v_and_b32_e32 v79, 0xffff0000, v249
	v_pk_fma_f32 v[60:61], v[64:65], s[28:29], v[60:61] op_sel_hi:[1,0,1]
	v_add_u32_e32 v64, s6, v144
	v_pk_fma_f32 v[112:113], v[142:143], s[28:29], v[112:113] op_sel_hi:[1,0,1]
	v_pk_fma_f32 v[142:143], v[74:75], s[28:29], v[70:71] op_sel_hi:[1,0,1]
	v_pk_fma_f32 v[140:141], v[72:73], s[28:29], v[68:69] op_sel_hi:[1,0,1]
	v_pk_fma_f32 v[138:139], v[78:79], s[28:29], v[66:67] op_sel_hi:[1,0,1]
	v_lshlrev_b32_e32 v66, 16, v253
	v_and_b32_e32 v67, 0xffff0000, v253
	v_lshlrev_b32_e32 v68, 16, v254
	v_and_b32_e32 v69, 0xffff0000, v254
	v_lshlrev_b32_e32 v70, 16, v255
	v_and_b32_e32 v71, 0xffff0000, v255
	v_ashrrev_i32_e32 v65, 31, v64
	v_pk_fma_f32 v[62:63], v[66:67], s[28:29], v[62:63] op_sel_hi:[1,0,1]
	v_pk_fma_f32 v[58:59], v[70:71], s[28:29], v[58:59] op_sel_hi:[1,0,1]
	v_pk_fma_f32 v[56:57], v[68:69], s[28:29], v[56:57] op_sel_hi:[1,0,1]
	v_lshlrev_b64 v[64:65], 2, v[64:65]
	v_lshl_add_u64 v[68:69], s[20:21], 0, v[64:65]
	v_lshl_add_u64 v[76:77], s[22:23], 0, v[64:65]
	global_load_dwordx4 v[144:147], v[68:69], off offset:16
	global_load_dwordx4 v[152:155], v[68:69], off
	global_load_dwordx4 v[148:151], v[76:77], off offset:16
	global_load_dwordx4 v[156:159], v[76:77], off
	global_load_dwordx4 v[64:67], v[68:69], off offset:528
	global_load_dwordx4 v[72:75], v[68:69], off offset:512
	s_nop 0
	global_load_dwordx4 v[68:71], v[76:77], off offset:528
	s_nop 0
	global_load_dwordx4 v[76:79], v[76:77], off offset:512
	v_pk_add_f32 v[188:189], v[100:101], v[88:89]
	v_pk_add_f32 v[190:191], v[30:31], v[18:19]
	v_pk_add_f32 v[192:193], v[28:29], v[16:17]
	v_pk_add_f32 v[174:175], v[174:175], v[190:191]
	v_pk_add_f32 v[188:189], v[188:189], v[192:193]
	v_add_f32_e32 v174, v174, v175
	v_add_f32_e32 v188, v188, v189
	v_add_f32_e32 v174, v188, v174
	v_mov_b32_e32 v175, v174
	s_nop 1
	v_permlane16_swap_b32_e32 v174, v175
	v_add_f32_e32 v174, v174, v175
	v_mov_b32_e32 v175, v174
	s_nop 1
	v_permlane32_swap_b32_e32 v174, v175
	v_add_f32_e32 v174, v174, v175
	v_fmamk_f32 v193, v174, 0xbc800000, v89
	v_fmamk_f32 v192, v174, 0xbc800000, v88
	v_fmamk_f32 v195, v174, 0xbc800000, v91
	v_fmamk_f32 v194, v174, 0xbc800000, v90
	v_fmamk_f32 v189, v174, 0xbc800000, v103
	v_fmamk_f32 v188, v174, 0xbc800000, v102
	v_fmamk_f32 v191, v174, 0xbc800000, v101
	v_fmamk_f32 v190, v174, 0xbc800000, v100
	v_fmamk_f32 v201, v174, 0xbc800000, v17
	v_fmamk_f32 v200, v174, 0xbc800000, v16
	v_fmamk_f32 v203, v174, 0xbc800000, v19
	v_fmamk_f32 v202, v174, 0xbc800000, v18
	v_pk_mul_f32 v[194:195], v[194:195], v[194:195]
	v_pk_mul_f32 v[192:193], v[192:193], v[192:193]
	v_fmamk_f32 v197, v174, 0xbc800000, v31
	v_fmamk_f32 v196, v174, 0xbc800000, v30
	v_fmamk_f32 v199, v174, 0xbc800000, v29
	v_fmamk_f32 v198, v174, 0xbc800000, v28
	v_pk_fma_f32 v[190:191], v[190:191], v[190:191], v[192:193]
	v_pk_fma_f32 v[188:189], v[188:189], v[188:189], v[194:195]
	v_pk_mul_f32 v[192:193], v[202:203], v[202:203]
	v_pk_mul_f32 v[194:195], v[200:201], v[200:201]
	v_pk_fma_f32 v[192:193], v[196:197], v[196:197], v[192:193]
	v_pk_fma_f32 v[194:195], v[198:199], v[198:199], v[194:195]
	v_pk_add_f32 v[188:189], v[188:189], v[192:193]
	v_pk_add_f32 v[190:191], v[190:191], v[194:195]
	v_add_f32_e32 v188, v188, v189
	v_add_f32_e32 v175, v190, v191
	v_add_f32_e32 v175, v175, v188
	v_mov_b32_e32 v188, v175
	s_nop 1
	v_permlane16_swap_b32_e32 v175, v188
	s_lshl_b32 s6, s9, 3
	v_add_f32_e32 v175, v175, v188
	s_add_i32 s11, s6, 0
	v_mov_b32_e32 v188, v175
	s_add_i32 s11, s11, 0x21000
	s_nop 0
	v_permlane32_swap_b32_e32 v175, v188
	s_and_saveexec_b64 s[6:7], vcc
	s_cbranch_execz .LBB0_1287
	s_lshl_b32 s15, s8, 11
	s_add_i32 s15, s11, s15
	v_mul_f32_e32 v174, 0x3c800000, v174
	v_add_f32_e32 v175, v175, v188
	v_lshl_add_u32 v188, v186, 5, s15
	ds_write_b64 v188, v[174:175]

.LBB0_1515:
	v_mov_b32_e32 v186, v177
	s_mov_b32 s8, s3
	v_mov_b32_e32 v187, v178
	s_mov_b32 s9, s72
	s_lshl_b32 s7, s14, 2
	s_ashr_i32 s10, s9, 1
	s_lshl_b32 s29, s8, 6
	s_add_i32 s38, s10, s7
	s_lshl_b32 s10, s40, 8
	s_lshl_b32 s6, s9, 5
	s_ashr_i32 s39, s38, 31
	s_add_i32 s31, s29, s10
	v_add_u32_e32 v128, s31, v186
	s_and_b32 s7, s6, 32
	s_lshl_b64 s[38:39], s[38:39], 22
	v_ashrrev_i32_e32 v129, 31, v128
	s_add_u32 s38, s58, s38
	v_lshlrev_b64 v[128:129], 7, v[128:129]
	s_addc_u32 s39, s59, s39
	v_lshlrev_b32_e32 v144, 3, v187
	v_lshl_add_u64 v[128:129], s[38:39], 0, v[128:129]
	s_lshl_b32 s12, s7, 1
	v_ashrrev_i32_e32 v145, 31, v144
	v_lshl_add_u64 v[128:129], v[128:129], 0, s[12:13]
	v_lshl_add_u64 v[132:133], v[144:145], 1, v[128:129]
	v_add_co_u32_e32 v128, vcc, s75, v132
	global_load_dwordx4 v[134:137], v[132:133], off
	global_load_dwordx4 v[138:141], v[132:133], off offset:2048
	v_addc_co_u32_e32 v129, vcc, 0, v133, vcc
	v_add_co_u32_e32 v130, vcc, s73, v132
	global_load_dwordx4 v[146:149], v[128:129], off offset:-4096
	s_nop 0
	v_addc_co_u32_e32 v131, vcc, 0, v133, vcc
	global_load_dwordx4 v[150:153], v[130:131], off offset:2048
	v_add_co_u32_e32 v130, vcc, s74, v132
	s_lshl_b32 s7, s14, 8
	s_nop 0
	v_addc_co_u32_e32 v131, vcc, 0, v133, vcc
	global_load_dwordx4 v[154:157], v[130:131], off
	global_load_dwordx4 v[188:191], v[128:129], off
	global_load_dwordx4 v[192:195], v[130:131], off offset:2048
	s_nop 0
	global_load_dwordx4 v[128:131], v[128:129], off offset:2048
	s_add_i32 s6, s6, s7
	s_mov_b32 s101, 0
	s_mov_b32 s100, s88
	v_lshl_add_u64 v[246:247], v[132:133], 0, s[100:101]
	s_mov_b32 s100, s96
	v_lshl_add_u64 v[252:253], v[132:133], 0, s[100:101]
	s_mov_b32 s100, s2
	v_lshl_add_u64 v[230:231], v[132:133], 0, s[100:101]
	s_mov_b32 s100, s78
	v_lshl_add_u64 v[234:235], v[132:133], 0, s[100:101]
	global_load_dwordx4 v[222:225], v[246:247], off offset:-4096
	global_load_dwordx4 v[226:229], v[252:253], off offset:-4096
	global_load_dwordx4 v[230:233], v[230:231], off offset:2048
	global_load_dwordx4 v[234:237], v[234:235], off offset:2048
	global_load_dwordx4 v[238:241], v[246:247], off
	global_load_dwordx4 v[242:245], v[252:253], off
	global_load_dwordx4 v[246:249], v[246:247], off offset:2048
	global_load_dwordx4 v[252:255], v[252:253], off offset:2048
	s_waitcnt vmcnt(8)
	v_lshlrev_b32_e32 v142, 16, v134
	v_and_b32_e32 v143, 0xffff0000, v134
	v_lshlrev_b32_e32 v134, 16, v135
	v_and_b32_e32 v135, 0xffff0000, v135
	v_lshlrev_b32_e32 v158, 16, v136
	v_and_b32_e32 v159, 0xffff0000, v136
	v_lshlrev_b32_e32 v136, 16, v137
	v_and_b32_e32 v137, 0xffff0000, v137
	v_lshlrev_b32_e32 v174, 16, v138
	v_and_b32_e32 v175, 0xffff0000, v138
	v_lshlrev_b32_e32 v138, 16, v139
	v_and_b32_e32 v139, 0xffff0000, v139
	v_lshlrev_b32_e32 v196, 16, v140
	v_and_b32_e32 v197, 0xffff0000, v140
	v_lshlrev_b32_e32 v140, 16, v141
	v_and_b32_e32 v141, 0xffff0000, v141
	v_pk_fma_f32 v[102:103], v[134:135], s[26:27], v[102:103] op_sel_hi:[1,0,1]
	v_pk_fma_f32 v[90:91], v[136:137], s[26:27], v[90:91] op_sel_hi:[1,0,1]
	v_lshlrev_b32_e32 v134, 16, v146
	v_and_b32_e32 v135, 0xffff0000, v146
	v_lshlrev_b32_e32 v136, 16, v147
	v_and_b32_e32 v137, 0xffff0000, v147
	v_pk_fma_f32 v[86:87], v[138:139], s[26:27], v[86:87] op_sel_hi:[1,0,1]
	v_pk_fma_f32 v[82:83], v[140:141], s[26:27], v[82:83] op_sel_hi:[1,0,1]
	v_lshlrev_b32_e32 v138, 16, v150
	v_and_b32_e32 v139, 0xffff0000, v150
	v_lshlrev_b32_e32 v140, 16, v151
	v_and_b32_e32 v141, 0xffff0000, v151
	v_pk_fma_f32 v[30:31], v[136:137], s[26:27], v[30:31] op_sel_hi:[1,0,1]
	v_pk_fma_f32 v[28:29], v[134:135], s[26:27], v[28:29] op_sel_hi:[1,0,1]
	v_lshlrev_b32_e32 v134, 16, v154
	v_and_b32_e32 v135, 0xffff0000, v154
	v_lshlrev_b32_e32 v136, 16, v155
	v_and_b32_e32 v137, 0xffff0000, v155
	v_pk_fma_f32 v[100:101], v[142:143], s[26:27], v[100:101] op_sel_hi:[1,0,1]
	v_lshlrev_b32_e32 v142, 16, v148
	v_and_b32_e32 v143, 0xffff0000, v148
	v_pk_fma_f32 v[6:7], v[140:141], s[26:27], v[6:7] op_sel_hi:[1,0,1]
	v_pk_fma_f32 v[4:5], v[138:139], s[26:27], v[4:5] op_sel_hi:[1,0,1]
	v_lshlrev_b32_e32 v138, 16, v156
	v_and_b32_e32 v139, 0xffff0000, v156
	v_lshlrev_b32_e32 v140, 16, v157
	v_and_b32_e32 v141, 0xffff0000, v157
	v_pk_fma_f32 v[98:99], v[136:137], s[26:27], v[98:99] op_sel_hi:[1,0,1]
	v_pk_fma_f32 v[96:97], v[134:135], s[26:27], v[96:97] op_sel_hi:[1,0,1]
	v_lshlrev_b32_e32 v134, 16, v188
	v_and_b32_e32 v135, 0xffff0000, v188
	v_lshlrev_b32_e32 v136, 16, v189
	v_and_b32_e32 v137, 0xffff0000, v189
	v_pk_fma_f32 v[16:17], v[142:143], s[26:27], v[16:17] op_sel_hi:[1,0,1]
	v_pk_fma_f32 v[94:95], v[140:141], s[26:27], v[94:95] op_sel_hi:[1,0,1]
	v_pk_fma_f32 v[92:93], v[138:139], s[26:27], v[92:93] op_sel_hi:[1,0,1]
	v_lshlrev_b32_e32 v138, 16, v190
	v_and_b32_e32 v139, 0xffff0000, v190
	v_lshlrev_b32_e32 v140, 16, v191
	v_and_b32_e32 v141, 0xffff0000, v191
	v_pk_fma_f32 v[14:15], v[136:137], s[26:27], v[14:15] op_sel_hi:[1,0,1]
	v_pk_fma_f32 v[12:13], v[134:135], s[26:27], v[12:13] op_sel_hi:[1,0,1]
	v_lshlrev_b32_e32 v134, 16, v192
	v_and_b32_e32 v135, 0xffff0000, v192
	v_lshlrev_b32_e32 v136, 16, v193
	v_and_b32_e32 v137, 0xffff0000, v193
	v_add_co_u32_e32 v142, vcc, s88, v132
	v_lshlrev_b32_e32 v146, 16, v149
	v_and_b32_e32 v147, 0xffff0000, v149
	v_lshlrev_b32_e32 v148, 16, v152
	v_and_b32_e32 v149, 0xffff0000, v152
	v_lshlrev_b32_e32 v150, 16, v153
	v_and_b32_e32 v151, 0xffff0000, v153
	v_pk_fma_f32 v[10:11], v[140:141], s[26:27], v[10:11] op_sel_hi:[1,0,1]
	v_pk_fma_f32 v[8:9], v[138:139], s[26:27], v[8:9] op_sel_hi:[1,0,1]
	v_lshlrev_b32_e32 v138, 16, v194
	v_and_b32_e32 v139, 0xffff0000, v194
	v_lshlrev_b32_e32 v140, 16, v195
	v_and_b32_e32 v141, 0xffff0000, v195
	v_pk_fma_f32 v[110:111], v[136:137], s[26:27], v[110:111] op_sel_hi:[1,0,1]
	v_pk_fma_f32 v[108:109], v[134:135], s[26:27], v[108:109] op_sel_hi:[1,0,1]
	v_lshlrev_b32_e32 v134, 16, v128
	v_and_b32_e32 v135, 0xffff0000, v128
	v_lshlrev_b32_e32 v128, 16, v129
	v_and_b32_e32 v129, 0xffff0000, v129
	v_lshlrev_b32_e32 v136, 16, v130
	v_and_b32_e32 v137, 0xffff0000, v130
	v_lshlrev_b32_e32 v130, 16, v131
	v_and_b32_e32 v131, 0xffff0000, v131
	v_addc_co_u32_e32 v143, vcc, 0, v133, vcc
	v_pk_fma_f32 v[88:89], v[158:159], s[26:27], v[88:89] op_sel_hi:[1,0,1]
	v_pk_fma_f32 v[84:85], v[174:175], s[26:27], v[84:85] op_sel_hi:[1,0,1]
	v_pk_fma_f32 v[80:81], v[196:197], s[26:27], v[80:81] op_sel_hi:[1,0,1]
	v_pk_fma_f32 v[18:19], v[146:147], s[26:27], v[18:19] op_sel_hi:[1,0,1]
	v_pk_fma_f32 v[2:3], v[150:151], s[26:27], v[2:3] op_sel_hi:[1,0,1]
	v_pk_fma_f32 v[0:1], v[148:149], s[26:27], v[0:1] op_sel_hi:[1,0,1]
	v_pk_fma_f32 v[106:107], v[140:141], s[26:27], v[106:107] op_sel_hi:[1,0,1]
	v_pk_fma_f32 v[104:105], v[138:139], s[26:27], v[104:105] op_sel_hi:[1,0,1]
	v_pk_fma_f32 v[26:27], v[128:129], s[26:27], v[26:27] op_sel_hi:[1,0,1]
	v_pk_fma_f32 v[24:25], v[134:135], s[26:27], v[24:25] op_sel_hi:[1,0,1]
	v_pk_fma_f32 v[22:23], v[130:131], s[26:27], v[22:23] op_sel_hi:[1,0,1]
	v_pk_fma_f32 v[20:21], v[136:137], s[26:27], v[20:21] op_sel_hi:[1,0,1]
	v_add_co_u32_e32 v158, vcc, s96, v132
	s_nop 1
	v_addc_co_u32_e32 v159, vcc, 0, v133, vcc
	v_add_co_u32_e32 v138, vcc, s2, v132
	s_nop 0
	v_addc_co_u32_e32 v139, vcc, 0, v133, vcc
	v_add_co_u32_e32 v132, vcc, s78, v132
	v_pk_add_f32 v[174:175], v[102:103], v[90:91]
	s_nop 0
	v_addc_co_u32_e32 v133, vcc, 0, v133, vcc
	v_cmp_eq_u32_e32 vcc, 0, v187
	s_waitcnt vmcnt(7)
	v_lshlrev_b32_e32 v132, 16, v222
	v_and_b32_e32 v133, 0xffff0000, v222
	v_lshlrev_b32_e32 v128, 16, v223
	v_and_b32_e32 v129, 0xffff0000, v223
	v_pk_fma_f32 v[118:119], v[128:129], s[26:27], v[118:119] op_sel_hi:[1,0,1]
	s_waitcnt vmcnt(6)
	v_lshlrev_b32_e32 v128, 16, v226
	v_and_b32_e32 v129, 0xffff0000, v226
	v_lshlrev_b32_e32 v142, 16, v224
	v_and_b32_e32 v143, 0xffff0000, v224
	v_lshlrev_b32_e32 v130, 16, v225
	v_and_b32_e32 v131, 0xffff0000, v225
	v_pk_fma_f32 v[116:117], v[132:133], s[26:27], v[116:117] op_sel_hi:[1,0,1]
	v_lshlrev_b32_e32 v132, 16, v228
	v_and_b32_e32 v133, 0xffff0000, v228
	v_pk_fma_f32 v[36:37], v[128:129], s[26:27], v[36:37] op_sel_hi:[1,0,1]
	s_waitcnt vmcnt(5)
	v_lshlrev_b32_e32 v128, 16, v230
	v_and_b32_e32 v129, 0xffff0000, v230
	v_pk_fma_f32 v[114:115], v[130:131], s[26:27], v[114:115] op_sel_hi:[1,0,1]
	v_lshlrev_b32_e32 v130, 16, v227
	v_and_b32_e32 v131, 0xffff0000, v227
	v_pk_fma_f32 v[32:33], v[132:133], s[26:27], v[32:33] op_sel_hi:[1,0,1]
	v_lshlrev_b32_e32 v132, 16, v232
	v_and_b32_e32 v133, 0xffff0000, v232
	v_pk_fma_f32 v[124:125], v[128:129], s[26:27], v[124:125] op_sel_hi:[1,0,1]
	s_waitcnt vmcnt(4)
	v_lshlrev_b32_e32 v128, 16, v234
	v_and_b32_e32 v129, 0xffff0000, v234
	v_lshlrev_b32_e32 v134, 16, v229
	v_and_b32_e32 v135, 0xffff0000, v229
	v_pk_fma_f32 v[38:39], v[130:131], s[26:27], v[38:39] op_sel_hi:[1,0,1]
	v_lshlrev_b32_e32 v130, 16, v231
	v_and_b32_e32 v131, 0xffff0000, v231
	v_pk_fma_f32 v[120:121], v[132:133], s[26:27], v[120:121] op_sel_hi:[1,0,1]
	v_lshlrev_b32_e32 v132, 16, v236
	v_and_b32_e32 v133, 0xffff0000, v236
	v_pk_fma_f32 v[44:45], v[128:129], s[26:27], v[44:45] op_sel_hi:[1,0,1]
	s_waitcnt vmcnt(3)
	v_lshlrev_b32_e32 v128, 16, v238
	v_and_b32_e32 v129, 0xffff0000, v238
	v_pk_fma_f32 v[34:35], v[134:135], s[26:27], v[34:35] op_sel_hi:[1,0,1]
	v_lshlrev_b32_e32 v134, 16, v233
	v_and_b32_e32 v135, 0xffff0000, v233
	v_pk_fma_f32 v[126:127], v[130:131], s[26:27], v[126:127] op_sel_hi:[1,0,1]
	v_lshlrev_b32_e32 v130, 16, v235
	v_and_b32_e32 v131, 0xffff0000, v235
	v_pk_fma_f32 v[40:41], v[132:133], s[26:27], v[40:41] op_sel_hi:[1,0,1]
	v_pk_fma_f32 v[132:133], v[128:129], s[26:27], v[76:77] op_sel_hi:[1,0,1]
	s_waitcnt vmcnt(2)
	v_lshlrev_b32_e32 v76, 16, v244
	v_and_b32_e32 v77, 0xffff0000, v244
	v_pk_fma_f32 v[122:123], v[134:135], s[26:27], v[122:123] op_sel_hi:[1,0,1]
	v_lshlrev_b32_e32 v134, 16, v237
	v_and_b32_e32 v135, 0xffff0000, v237
	v_pk_fma_f32 v[46:47], v[130:131], s[26:27], v[46:47] op_sel_hi:[1,0,1]
	v_lshlrev_b32_e32 v130, 16, v239
	v_and_b32_e32 v131, 0xffff0000, v239
	v_lshlrev_b32_e32 v136, 16, v240
	v_and_b32_e32 v137, 0xffff0000, v240
	v_lshlrev_b32_e32 v138, 16, v241
	v_and_b32_e32 v139, 0xffff0000, v241
	v_pk_fma_f32 v[48:49], v[76:77], s[26:27], v[48:49] op_sel_hi:[1,0,1]
	s_waitcnt vmcnt(1)
	v_lshlrev_b32_e32 v76, 16, v248
	v_and_b32_e32 v77, 0xffff0000, v248
	v_pk_fma_f32 v[42:43], v[134:135], s[26:27], v[42:43] op_sel_hi:[1,0,1]
	v_pk_fma_f32 v[134:135], v[130:131], s[26:27], v[78:79] op_sel_hi:[1,0,1]
	v_pk_fma_f32 v[130:131], v[138:139], s[26:27], v[74:75] op_sel_hi:[1,0,1]
	v_pk_fma_f32 v[128:129], v[136:137], s[26:27], v[72:73] op_sel_hi:[1,0,1]
	v_lshlrev_b32_e32 v72, 16, v242
	v_and_b32_e32 v73, 0xffff0000, v242
	v_lshlrev_b32_e32 v74, 16, v243
	v_and_b32_e32 v75, 0xffff0000, v243
	v_lshlrev_b32_e32 v78, 16, v245
	v_and_b32_e32 v79, 0xffff0000, v245
	v_pk_fma_f32 v[136:137], v[76:77], s[26:27], v[64:65] op_sel_hi:[1,0,1]
	s_waitcnt vmcnt(0)
	v_lshlrev_b32_e32 v64, 16, v252
	v_and_b32_e32 v65, 0xffff0000, v252
	v_pk_fma_f32 v[54:55], v[74:75], s[26:27], v[54:55] op_sel_hi:[1,0,1]
	v_pk_fma_f32 v[52:53], v[72:73], s[26:27], v[52:53] op_sel_hi:[1,0,1]
	v_pk_fma_f32 v[50:51], v[78:79], s[26:27], v[50:51] op_sel_hi:[1,0,1]
	v_lshlrev_b32_e32 v72, 16, v246
	v_and_b32_e32 v73, 0xffff0000, v246
	v_lshlrev_b32_e32 v74, 16, v247
	v_and_b32_e32 v75, 0xffff0000, v247
	v_lshlrev_b32_e32 v78, 16, v249
	v_and_b32_e32 v79, 0xffff0000, v249
	v_pk_fma_f32 v[60:61], v[64:65], s[26:27], v[60:61] op_sel_hi:[1,0,1]
	v_add_u32_e32 v64, s6, v144
	v_pk_fma_f32 v[112:113], v[142:143], s[26:27], v[112:113] op_sel_hi:[1,0,1]
	v_pk_fma_f32 v[142:143], v[74:75], s[26:27], v[70:71] op_sel_hi:[1,0,1]
	v_pk_fma_f32 v[140:141], v[72:73], s[26:27], v[68:69] op_sel_hi:[1,0,1]
	v_pk_fma_f32 v[138:139], v[78:79], s[26:27], v[66:67] op_sel_hi:[1,0,1]
	v_lshlrev_b32_e32 v66, 16, v253
	v_and_b32_e32 v67, 0xffff0000, v253
	v_lshlrev_b32_e32 v68, 16, v254
	v_and_b32_e32 v69, 0xffff0000, v254
	v_lshlrev_b32_e32 v70, 16, v255
	v_and_b32_e32 v71, 0xffff0000, v255
	v_ashrrev_i32_e32 v65, 31, v64
	v_pk_fma_f32 v[62:63], v[66:67], s[26:27], v[62:63] op_sel_hi:[1,0,1]
	v_pk_fma_f32 v[58:59], v[70:71], s[26:27], v[58:59] op_sel_hi:[1,0,1]
	v_pk_fma_f32 v[56:57], v[68:69], s[26:27], v[56:57] op_sel_hi:[1,0,1]
	v_lshlrev_b64 v[64:65], 2, v[64:65]
	v_lshl_add_u64 v[68:69], s[18:19], 0, v[64:65]
	v_lshl_add_u64 v[76:77], s[20:21], 0, v[64:65]
	global_load_dwordx4 v[144:147], v[68:69], off offset:16
	global_load_dwordx4 v[152:155], v[68:69], off
	global_load_dwordx4 v[148:151], v[76:77], off offset:16
	global_load_dwordx4 v[156:159], v[76:77], off
	global_load_dwordx4 v[64:67], v[68:69], off offset:528
	global_load_dwordx4 v[72:75], v[68:69], off offset:512
	s_nop 0
	global_load_dwordx4 v[68:71], v[76:77], off offset:528
	s_nop 0
	global_load_dwordx4 v[76:79], v[76:77], off offset:512
	v_pk_add_f32 v[188:189], v[100:101], v[88:89]
	v_pk_add_f32 v[190:191], v[30:31], v[18:19]
	v_pk_add_f32 v[192:193], v[28:29], v[16:17]
	v_pk_add_f32 v[174:175], v[174:175], v[190:191]
	v_pk_add_f32 v[188:189], v[188:189], v[192:193]
	v_add_f32_e32 v174, v174, v175
	v_add_f32_e32 v188, v188, v189
	v_add_f32_e32 v174, v188, v174
	v_mov_b32_e32 v175, v174
	s_nop 1
	v_permlane16_swap_b32_e32 v174, v175
	v_add_f32_e32 v174, v174, v175
	v_mov_b32_e32 v175, v174
	s_nop 1
	v_permlane32_swap_b32_e32 v174, v175
	v_add_f32_e32 v174, v174, v175
	v_fmamk_f32 v193, v174, 0xbc800000, v89
	v_fmamk_f32 v192, v174, 0xbc800000, v88
	v_fmamk_f32 v195, v174, 0xbc800000, v91
	v_fmamk_f32 v194, v174, 0xbc800000, v90
	v_fmamk_f32 v189, v174, 0xbc800000, v103
	v_fmamk_f32 v188, v174, 0xbc800000, v102
	v_fmamk_f32 v191, v174, 0xbc800000, v101
	v_fmamk_f32 v190, v174, 0xbc800000, v100
	v_fmamk_f32 v201, v174, 0xbc800000, v17
	v_fmamk_f32 v200, v174, 0xbc800000, v16
	v_fmamk_f32 v203, v174, 0xbc800000, v19
	v_fmamk_f32 v202, v174, 0xbc800000, v18
	v_pk_mul_f32 v[194:195], v[194:195], v[194:195]
	v_pk_mul_f32 v[192:193], v[192:193], v[192:193]
	v_fmamk_f32 v197, v174, 0xbc800000, v31
	v_fmamk_f32 v196, v174, 0xbc800000, v30
	v_fmamk_f32 v199, v174, 0xbc800000, v29
	v_fmamk_f32 v198, v174, 0xbc800000, v28
	v_pk_fma_f32 v[190:191], v[190:191], v[190:191], v[192:193]
	v_pk_fma_f32 v[188:189], v[188:189], v[188:189], v[194:195]
	v_pk_mul_f32 v[192:193], v[202:203], v[202:203]
	v_pk_mul_f32 v[194:195], v[200:201], v[200:201]
	v_pk_fma_f32 v[192:193], v[196:197], v[196:197], v[192:193]
	v_pk_fma_f32 v[194:195], v[198:199], v[198:199], v[194:195]
	v_pk_add_f32 v[188:189], v[188:189], v[192:193]
	v_pk_add_f32 v[190:191], v[190:191], v[194:195]
	v_add_f32_e32 v188, v188, v189
	v_add_f32_e32 v175, v190, v191
	v_add_f32_e32 v175, v175, v188
	v_mov_b32_e32 v188, v175
	s_nop 1
	v_permlane16_swap_b32_e32 v175, v188
	s_lshl_b32 s6, s9, 3
	v_add_f32_e32 v175, v175, v188
	s_add_i32 s11, s6, 0
	v_mov_b32_e32 v188, v175
	s_add_i32 s11, s11, 0x21000
	s_nop 0
	v_permlane32_swap_b32_e32 v175, v188
	s_and_saveexec_b64 s[6:7], vcc
	s_cbranch_execz .LBB0_1517
	s_lshl_b32 s15, s8, 11
	s_add_i32 s15, s11, s15
	v_mul_f32_e32 v174, 0x3c800000, v174
	v_add_f32_e32 v175, v175, v188
	v_lshl_add_u32 v188, v186, 5, s15
	ds_write_b64 v188, v[174:175]

.LBB0_1709:
	v_mov_b32_e32 v187, v178
	s_mov_b32 s8, s4
	v_mov_b32_e32 v186, v177
	s_mov_b32 s9, s55
	s_lshl_b32 s7, s14, 2
	s_ashr_i32 s10, s8, 1
	s_lshl_b32 s31, s9, 6
	s_add_i32 s38, s10, s7
	s_lshl_b32 s10, s40, 8
	s_lshl_b32 s6, s8, 5
	s_ashr_i32 s39, s38, 31
	s_add_i32 s51, s31, s10
	v_add_u32_e32 v128, s51, v186
	s_and_b32 s7, s6, 32
	s_lshl_b64 s[38:39], s[38:39], 22
	v_ashrrev_i32_e32 v129, 31, v128
	s_add_u32 s38, s58, s38
	v_lshlrev_b64 v[128:129], 7, v[128:129]
	s_addc_u32 s39, s59, s39
	v_lshlrev_b32_e32 v148, 3, v187
	v_lshl_add_u64 v[128:129], s[38:39], 0, v[128:129]
	s_lshl_b32 s12, s7, 1
	v_ashrrev_i32_e32 v149, 31, v148
	v_lshl_add_u64 v[128:129], v[128:129], 0, s[12:13]
	v_lshl_add_u64 v[128:129], v[148:149], 1, v[128:129]
	v_add_co_u32_e32 v146, vcc, s69, v128
	global_load_dwordx4 v[130:133], v[128:129], off
	global_load_dwordx4 v[134:137], v[128:129], off offset:2048
	v_addc_co_u32_e32 v147, vcc, 0, v129, vcc
	v_add_co_u32_e32 v142, vcc, s33, v128
	global_load_dwordx4 v[138:141], v[146:147], off offset:-4096
	s_nop 0
	v_addc_co_u32_e32 v143, vcc, 0, v129, vcc
	global_load_dwordx4 v[142:145], v[142:143], off offset:2048
	v_add_co_u32_e32 v158, vcc, s56, v128
	global_load_dwordx4 v[154:157], v[146:147], off
	s_nop 0
	v_addc_co_u32_e32 v159, vcc, 0, v129, vcc
	global_load_dwordx4 v[150:153], v[158:159], off
	global_load_dwordx4 v[188:191], v[158:159], off offset:2048
	global_load_dwordx4 v[192:195], v[146:147], off offset:2048
	v_pk_mul_f32 v[90:91], v[90:91], 0.5 op_sel_hi:[1,0]
	v_pk_mul_f32 v[88:89], v[88:89], 0.5 op_sel_hi:[1,0]
	v_pk_mul_f32 v[174:175], v[86:87], 0.5 op_sel_hi:[1,0]
	v_pk_mul_f32 v[196:197], v[84:85], 0.5 op_sel_hi:[1,0]
	v_pk_mul_f32 v[198:199], v[82:83], 0.5 op_sel_hi:[1,0]
	v_pk_mul_f32 v[200:201], v[80:81], 0.5 op_sel_hi:[1,0]
	v_pk_mul_f32 v[14:15], v[14:15], 0.5 op_sel_hi:[1,0]
	v_pk_mul_f32 v[12:13], v[12:13], 0.5 op_sel_hi:[1,0]
	v_pk_mul_f32 v[94:95], v[94:95], 0.5 op_sel_hi:[1,0]
	v_pk_mul_f32 v[92:93], v[92:93], 0.5 op_sel_hi:[1,0]
	v_pk_mul_f32 v[10:11], v[10:11], 0.5 op_sel_hi:[1,0]
	v_pk_mul_f32 v[8:9], v[8:9], 0.5 op_sel_hi:[1,0]
	s_lshl_b32 s7, s14, 8
	s_add_i32 s6, s6, s7
	s_mov_b32 s101, 0
	s_mov_b32 s100, s71
	v_lshl_add_u64 v[242:243], v[128:129], 0, s[100:101]
	s_mov_b32 s100, s78
	v_lshl_add_u64 v[252:253], v[128:129], 0, s[100:101]
	s_mov_b32 s100, s3
	v_lshl_add_u64 v[230:231], v[128:129], 0, s[100:101]
	s_mov_b32 s100, s70
	v_lshl_add_u64 v[234:235], v[128:129], 0, s[100:101]
	global_load_dwordx4 v[222:225], v[242:243], off offset:-4096
	global_load_dwordx4 v[226:229], v[252:253], off offset:-4096
	global_load_dwordx4 v[230:233], v[230:231], off offset:2048
	global_load_dwordx4 v[234:237], v[234:235], off offset:2048
	global_load_dwordx4 v[238:241], v[242:243], off
	global_load_dwordx4 v[242:245], v[242:243], off offset:2048
	global_load_dwordx4 v[246:249], v[252:253], off
	global_load_dwordx4 v[252:255], v[252:253], off offset:2048
	s_waitcnt vmcnt(8)
	v_lshlrev_b32_e32 v80, 16, v130
	v_and_b32_e32 v81, 0xffff0000, v130
	v_lshlrev_b32_e32 v82, 16, v131
	v_and_b32_e32 v83, 0xffff0000, v131
	v_lshlrev_b32_e32 v84, 16, v132
	v_and_b32_e32 v85, 0xffff0000, v132
	v_lshlrev_b32_e32 v86, 16, v133
	v_and_b32_e32 v87, 0xffff0000, v133
	v_lshlrev_b32_e32 v130, 16, v134
	v_and_b32_e32 v131, 0xffff0000, v134
	v_lshlrev_b32_e32 v132, 16, v135
	v_and_b32_e32 v133, 0xffff0000, v135
	v_lshlrev_b32_e32 v134, 16, v136
	v_and_b32_e32 v135, 0xffff0000, v136
	v_lshlrev_b32_e32 v136, 16, v137
	v_and_b32_e32 v137, 0xffff0000, v137
	v_pk_fma_f32 v[90:91], v[86:87], s[28:29], v[90:91] op_sel_hi:[1,0,1]
	v_pk_fma_f32 v[88:89], v[84:85], s[28:29], v[88:89] op_sel_hi:[1,0,1]
	v_pk_fma_f32 v[86:87], v[132:133], s[28:29], v[14:15] op_sel_hi:[1,0,1]
	v_pk_fma_f32 v[84:85], v[130:131], s[28:29], v[12:13] op_sel_hi:[1,0,1]
	v_lshlrev_b32_e32 v130, 16, v142
	v_and_b32_e32 v131, 0xffff0000, v142
	v_lshlrev_b32_e32 v132, 16, v143
	v_and_b32_e32 v133, 0xffff0000, v143
	v_pk_fma_f32 v[94:95], v[82:83], s[28:29], v[94:95] op_sel_hi:[1,0,1]
	v_pk_fma_f32 v[92:93], v[80:81], s[28:29], v[92:93] op_sel_hi:[1,0,1]
	v_pk_fma_f32 v[82:83], v[136:137], s[28:29], v[10:11] op_sel_hi:[1,0,1]
	v_pk_fma_f32 v[80:81], v[134:135], s[28:29], v[8:9] op_sel_hi:[1,0,1]
	v_lshlrev_b32_e32 v134, 16, v144
	v_and_b32_e32 v135, 0xffff0000, v144
	v_lshlrev_b32_e32 v136, 16, v145
	v_and_b32_e32 v137, 0xffff0000, v145
	v_pk_mul_f32 v[130:131], v[130:131], s[28:29] op_sel_hi:[1,0]
	v_pk_mul_f32 v[132:133], v[132:133], s[28:29] op_sel_hi:[1,0]
	v_pk_fma_f32 v[4:5], v[4:5], 0.5, v[130:131] op_sel_hi:[1,0,1]
	v_pk_fma_f32 v[6:7], v[6:7], 0.5, v[132:133] op_sel_hi:[1,0,1]
	v_pk_mul_f32 v[130:131], v[134:135], s[28:29] op_sel_hi:[1,0]
	v_pk_mul_f32 v[132:133], v[136:137], s[28:29] op_sel_hi:[1,0]
	v_pk_fma_f32 v[0:1], v[0:1], 0.5, v[130:131] op_sel_hi:[1,0,1]
	v_pk_fma_f32 v[2:3], v[2:3], 0.5, v[132:133] op_sel_hi:[1,0,1]
	v_lshlrev_b32_e32 v130, 16, v150
	v_and_b32_e32 v131, 0xffff0000, v150
	v_lshlrev_b32_e32 v132, 16, v151
	v_and_b32_e32 v133, 0xffff0000, v151
	v_lshlrev_b32_e32 v134, 16, v152
	v_and_b32_e32 v135, 0xffff0000, v152
	v_lshlrev_b32_e32 v136, 16, v153
	v_and_b32_e32 v137, 0xffff0000, v153
	v_pk_mul_f32 v[130:131], v[130:131], s[28:29] op_sel_hi:[1,0]
	v_pk_mul_f32 v[132:133], v[132:133], s[28:29] op_sel_hi:[1,0]
	v_pk_fma_f32 v[100:101], v[100:101], 0.5, v[130:131] op_sel_hi:[1,0,1]
	v_pk_fma_f32 v[102:103], v[102:103], 0.5, v[132:133] op_sel_hi:[1,0,1]
	v_pk_mul_f32 v[130:131], v[134:135], s[28:29] op_sel_hi:[1,0]
	v_pk_mul_f32 v[132:133], v[136:137], s[28:29] op_sel_hi:[1,0]
	v_pk_fma_f32 v[96:97], v[96:97], 0.5, v[130:131] op_sel_hi:[1,0,1]
	v_pk_fma_f32 v[98:99], v[98:99], 0.5, v[132:133] op_sel_hi:[1,0,1]
	v_lshlrev_b32_e32 v130, 16, v154
	v_and_b32_e32 v131, 0xffff0000, v154
	v_lshlrev_b32_e32 v132, 16, v155
	v_and_b32_e32 v133, 0xffff0000, v155
	v_lshlrev_b32_e32 v134, 16, v156
	v_and_b32_e32 v135, 0xffff0000, v156
	v_lshlrev_b32_e32 v136, 16, v157
	v_and_b32_e32 v137, 0xffff0000, v157
	v_pk_mul_f32 v[130:131], v[130:131], s[28:29] op_sel_hi:[1,0]
	v_pk_mul_f32 v[132:133], v[132:133], s[28:29] op_sel_hi:[1,0]
	v_pk_fma_f32 v[20:21], v[20:21], 0.5, v[130:131] op_sel_hi:[1,0,1]
	v_pk_fma_f32 v[22:23], v[22:23], 0.5, v[132:133] op_sel_hi:[1,0,1]
	v_pk_mul_f32 v[130:131], v[134:135], s[28:29] op_sel_hi:[1,0]
	v_pk_mul_f32 v[132:133], v[136:137], s[28:29] op_sel_hi:[1,0]
	v_pk_fma_f32 v[16:17], v[16:17], 0.5, v[130:131] op_sel_hi:[1,0,1]
	v_pk_fma_f32 v[18:19], v[18:19], 0.5, v[132:133] op_sel_hi:[1,0,1]
	v_lshlrev_b32_e32 v130, 16, v188
	v_and_b32_e32 v131, 0xffff0000, v188
	v_lshlrev_b32_e32 v132, 16, v189
	v_and_b32_e32 v133, 0xffff0000, v189
	v_lshlrev_b32_e32 v134, 16, v190
	v_and_b32_e32 v135, 0xffff0000, v190
	v_lshlrev_b32_e32 v136, 16, v191
	v_and_b32_e32 v137, 0xffff0000, v191
	v_pk_mul_f32 v[130:131], v[130:131], s[28:29] op_sel_hi:[1,0]
	v_pk_mul_f32 v[132:133], v[132:133], s[28:29] op_sel_hi:[1,0]
	v_pk_fma_f32 v[108:109], v[108:109], 0.5, v[130:131] op_sel_hi:[1,0,1]
	v_pk_fma_f32 v[110:111], v[110:111], 0.5, v[132:133] op_sel_hi:[1,0,1]
	v_pk_mul_f32 v[130:131], v[134:135], s[28:29] op_sel_hi:[1,0]
	v_pk_mul_f32 v[132:133], v[136:137], s[28:29] op_sel_hi:[1,0]
	v_pk_fma_f32 v[104:105], v[104:105], 0.5, v[130:131] op_sel_hi:[1,0,1]
	v_pk_fma_f32 v[106:107], v[106:107], 0.5, v[132:133] op_sel_hi:[1,0,1]
	v_lshlrev_b32_e32 v130, 16, v192
	v_and_b32_e32 v131, 0xffff0000, v192
	v_lshlrev_b32_e32 v132, 16, v193
	v_and_b32_e32 v133, 0xffff0000, v193
	v_lshlrev_b32_e32 v134, 16, v194
	v_and_b32_e32 v135, 0xffff0000, v194
	v_lshlrev_b32_e32 v136, 16, v195
	v_and_b32_e32 v137, 0xffff0000, v195
	v_pk_mul_f32 v[130:131], v[130:131], s[28:29] op_sel_hi:[1,0]
	v_pk_mul_f32 v[132:133], v[132:133], s[28:29] op_sel_hi:[1,0]
	v_lshlrev_b32_e32 v146, 16, v138
	v_and_b32_e32 v147, 0xffff0000, v138
	v_lshlrev_b32_e32 v138, 16, v139
	v_and_b32_e32 v139, 0xffff0000, v139
	v_lshlrev_b32_e32 v158, 16, v140
	v_and_b32_e32 v159, 0xffff0000, v140
	v_lshlrev_b32_e32 v140, 16, v141
	v_and_b32_e32 v141, 0xffff0000, v141
	v_pk_fma_f32 v[30:31], v[30:31], 0.5, v[132:133] op_sel_hi:[1,0,1]
	v_pk_fma_f32 v[28:29], v[28:29], 0.5, v[130:131] op_sel_hi:[1,0,1]
	v_pk_mul_f32 v[130:131], v[134:135], s[28:29] op_sel_hi:[1,0]
	v_pk_mul_f32 v[132:133], v[136:137], s[28:29] op_sel_hi:[1,0]
	v_pk_fma_f32 v[14:15], v[138:139], s[28:29], v[174:175] op_sel_hi:[1,0,1]
	v_pk_fma_f32 v[12:13], v[146:147], s[28:29], v[196:197] op_sel_hi:[1,0,1]
	v_pk_fma_f32 v[10:11], v[140:141], s[28:29], v[198:199] op_sel_hi:[1,0,1]
	v_pk_fma_f32 v[8:9], v[158:159], s[28:29], v[200:201] op_sel_hi:[1,0,1]
	v_pk_fma_f32 v[26:27], v[26:27], 0.5, v[132:133] op_sel_hi:[1,0,1]
	v_pk_fma_f32 v[24:25], v[24:25], 0.5, v[130:131] op_sel_hi:[1,0,1]
	v_add_co_u32_e32 v142, vcc, s71, v128
	s_nop 1
	v_addc_co_u32_e32 v143, vcc, 0, v129, vcc
	v_add_co_u32_e32 v144, vcc, s78, v128
	v_pk_add_f32 v[174:175], v[94:95], v[90:91]
	s_nop 0
	v_addc_co_u32_e32 v145, vcc, 0, v129, vcc
	v_add_co_u32_e32 v138, vcc, s3, v128
	s_nop 1
	v_addc_co_u32_e32 v139, vcc, 0, v129, vcc
	v_add_co_u32_e32 v128, vcc, s70, v128
	s_nop 1
	v_addc_co_u32_e32 v129, vcc, 0, v129, vcc
	s_nop 0
	v_cmp_eq_u32_e32 vcc, 0, v187
	s_waitcnt vmcnt(7)
	v_lshlrev_b32_e32 v128, 16, v222
	v_and_b32_e32 v129, 0xffff0000, v222
	v_lshlrev_b32_e32 v142, 16, v224
	v_and_b32_e32 v143, 0xffff0000, v224
	v_pk_mul_f32 v[128:129], v[128:129], s[28:29] op_sel_hi:[1,0]
	v_lshlrev_b32_e32 v130, 16, v223
	v_and_b32_e32 v131, 0xffff0000, v223
	v_pk_fma_f32 v[116:117], v[116:117], 0.5, v[128:129] op_sel_hi:[1,0,1]
	v_pk_mul_f32 v[128:129], v[142:143], s[28:29] op_sel_hi:[1,0]
	v_lshlrev_b32_e32 v132, 16, v225
	v_and_b32_e32 v133, 0xffff0000, v225
	v_pk_mul_f32 v[130:131], v[130:131], s[28:29] op_sel_hi:[1,0]
	v_pk_fma_f32 v[112:113], v[112:113], 0.5, v[128:129] op_sel_hi:[1,0,1]
	s_waitcnt vmcnt(6)
	v_lshlrev_b32_e32 v128, 16, v226
	v_and_b32_e32 v129, 0xffff0000, v226
	v_pk_fma_f32 v[118:119], v[118:119], 0.5, v[130:131] op_sel_hi:[1,0,1]
	v_pk_mul_f32 v[130:131], v[132:133], s[28:29] op_sel_hi:[1,0]
	v_lshlrev_b32_e32 v132, 16, v228
	v_and_b32_e32 v133, 0xffff0000, v228
	v_pk_mul_f32 v[128:129], v[128:129], s[28:29] op_sel_hi:[1,0]
	v_pk_fma_f32 v[114:115], v[114:115], 0.5, v[130:131] op_sel_hi:[1,0,1]
	v_lshlrev_b32_e32 v130, 16, v227
	v_and_b32_e32 v131, 0xffff0000, v227
	v_pk_fma_f32 v[36:37], v[36:37], 0.5, v[128:129] op_sel_hi:[1,0,1]
	v_pk_mul_f32 v[128:129], v[132:133], s[28:29] op_sel_hi:[1,0]
	v_lshlrev_b32_e32 v134, 16, v229
	v_and_b32_e32 v135, 0xffff0000, v229
	v_pk_mul_f32 v[130:131], v[130:131], s[28:29] op_sel_hi:[1,0]
	v_pk_fma_f32 v[32:33], v[32:33], 0.5, v[128:129] op_sel_hi:[1,0,1]
	s_waitcnt vmcnt(5)
	v_lshlrev_b32_e32 v128, 16, v230
	v_and_b32_e32 v129, 0xffff0000, v230
	v_pk_fma_f32 v[38:39], v[38:39], 0.5, v[130:131] op_sel_hi:[1,0,1]
	v_pk_mul_f32 v[130:131], v[134:135], s[28:29] op_sel_hi:[1,0]
	v_lshlrev_b32_e32 v132, 16, v232
	v_and_b32_e32 v133, 0xffff0000, v232
	v_pk_mul_f32 v[128:129], v[128:129], s[28:29] op_sel_hi:[1,0]
	v_pk_fma_f32 v[34:35], v[34:35], 0.5, v[130:131] op_sel_hi:[1,0,1]
	v_lshlrev_b32_e32 v130, 16, v231
	v_and_b32_e32 v131, 0xffff0000, v231
	v_pk_fma_f32 v[124:125], v[124:125], 0.5, v[128:129] op_sel_hi:[1,0,1]
	v_pk_mul_f32 v[128:129], v[132:133], s[28:29] op_sel_hi:[1,0]
	v_lshlrev_b32_e32 v134, 16, v233
	v_and_b32_e32 v135, 0xffff0000, v233
	v_pk_mul_f32 v[130:131], v[130:131], s[28:29] op_sel_hi:[1,0]
	v_pk_fma_f32 v[120:121], v[120:121], 0.5, v[128:129] op_sel_hi:[1,0,1]
	s_waitcnt vmcnt(4)
	v_lshlrev_b32_e32 v128, 16, v234
	v_and_b32_e32 v129, 0xffff0000, v234
	v_pk_fma_f32 v[126:127], v[126:127], 0.5, v[130:131] op_sel_hi:[1,0,1]
	v_pk_mul_f32 v[130:131], v[134:135], s[28:29] op_sel_hi:[1,0]
	v_lshlrev_b32_e32 v132, 16, v236
	v_and_b32_e32 v133, 0xffff0000, v236
	v_pk_mul_f32 v[128:129], v[128:129], s[28:29] op_sel_hi:[1,0]
	v_pk_fma_f32 v[122:123], v[122:123], 0.5, v[130:131] op_sel_hi:[1,0,1]
	v_lshlrev_b32_e32 v130, 16, v235
	v_and_b32_e32 v131, 0xffff0000, v235
	v_pk_fma_f32 v[44:45], v[44:45], 0.5, v[128:129] op_sel_hi:[1,0,1]
	v_pk_mul_f32 v[128:129], v[132:133], s[28:29] op_sel_hi:[1,0]
	v_lshlrev_b32_e32 v134, 16, v237
	v_and_b32_e32 v135, 0xffff0000, v237
	v_pk_mul_f32 v[130:131], v[130:131], s[28:29] op_sel_hi:[1,0]
	v_pk_fma_f32 v[40:41], v[40:41], 0.5, v[128:129] op_sel_hi:[1,0,1]
	s_waitcnt vmcnt(3)
	v_lshlrev_b32_e32 v128, 16, v238
	v_and_b32_e32 v129, 0xffff0000, v238
	v_pk_fma_f32 v[46:47], v[46:47], 0.5, v[130:131] op_sel_hi:[1,0,1]
	v_pk_mul_f32 v[130:131], v[134:135], s[28:29] op_sel_hi:[1,0]
	v_lshlrev_b32_e32 v136, 16, v240
	v_and_b32_e32 v137, 0xffff0000, v240
	v_pk_mul_f32 v[128:129], v[128:129], s[28:29] op_sel_hi:[1,0]
	v_pk_fma_f32 v[42:43], v[42:43], 0.5, v[130:131] op_sel_hi:[1,0,1]
	v_lshlrev_b32_e32 v130, 16, v239
	v_and_b32_e32 v131, 0xffff0000, v239
	v_pk_fma_f32 v[132:133], v[76:77], 0.5, v[128:129] op_sel_hi:[1,0,1]
	v_pk_mul_f32 v[76:77], v[136:137], s[28:29] op_sel_hi:[1,0]
	v_lshlrev_b32_e32 v138, 16, v241
	v_and_b32_e32 v139, 0xffff0000, v241
	v_pk_mul_f32 v[130:131], v[130:131], s[28:29] op_sel_hi:[1,0]
	v_pk_fma_f32 v[128:129], v[72:73], 0.5, v[76:77] op_sel_hi:[1,0,1]
	s_waitcnt vmcnt(1)
	v_lshlrev_b32_e32 v72, 16, v246
	v_and_b32_e32 v73, 0xffff0000, v246
	v_pk_fma_f32 v[134:135], v[78:79], 0.5, v[130:131] op_sel_hi:[1,0,1]
	v_pk_mul_f32 v[78:79], v[138:139], s[28:29] op_sel_hi:[1,0]
	v_lshlrev_b32_e32 v76, 16, v248
	v_and_b32_e32 v77, 0xffff0000, v248
	v_pk_mul_f32 v[72:73], v[72:73], s[28:29] op_sel_hi:[1,0]
	v_pk_fma_f32 v[130:131], v[74:75], 0.5, v[78:79] op_sel_hi:[1,0,1]
	v_lshlrev_b32_e32 v74, 16, v247
	v_and_b32_e32 v75, 0xffff0000, v247
	v_pk_fma_f32 v[52:53], v[52:53], 0.5, v[72:73] op_sel_hi:[1,0,1]
	v_pk_mul_f32 v[72:73], v[76:77], s[28:29] op_sel_hi:[1,0]
	v_lshlrev_b32_e32 v78, 16, v249
	v_and_b32_e32 v79, 0xffff0000, v249
	v_pk_mul_f32 v[74:75], v[74:75], s[28:29] op_sel_hi:[1,0]
	v_pk_fma_f32 v[48:49], v[48:49], 0.5, v[72:73] op_sel_hi:[1,0,1]
	v_lshlrev_b32_e32 v72, 16, v242
	v_and_b32_e32 v73, 0xffff0000, v242
	v_pk_fma_f32 v[54:55], v[54:55], 0.5, v[74:75] op_sel_hi:[1,0,1]
	v_pk_mul_f32 v[74:75], v[78:79], s[28:29] op_sel_hi:[1,0]
	v_lshlrev_b32_e32 v76, 16, v244
	v_and_b32_e32 v77, 0xffff0000, v244
	v_pk_mul_f32 v[72:73], v[72:73], s[28:29] op_sel_hi:[1,0]
	v_pk_fma_f32 v[50:51], v[50:51], 0.5, v[74:75] op_sel_hi:[1,0,1]
	v_lshlrev_b32_e32 v74, 16, v243
	v_and_b32_e32 v75, 0xffff0000, v243
	v_pk_fma_f32 v[140:141], v[68:69], 0.5, v[72:73] op_sel_hi:[1,0,1]
	v_pk_mul_f32 v[68:69], v[76:77], s[28:29] op_sel_hi:[1,0]
	v_lshlrev_b32_e32 v78, 16, v245
	v_and_b32_e32 v79, 0xffff0000, v245
	v_pk_mul_f32 v[74:75], v[74:75], s[28:29] op_sel_hi:[1,0]
	v_pk_fma_f32 v[136:137], v[64:65], 0.5, v[68:69] op_sel_hi:[1,0,1]
	s_waitcnt vmcnt(0)
	v_lshlrev_b32_e32 v64, 16, v252
	v_and_b32_e32 v65, 0xffff0000, v252
	v_pk_fma_f32 v[142:143], v[70:71], 0.5, v[74:75] op_sel_hi:[1,0,1]
	v_pk_mul_f32 v[70:71], v[78:79], s[28:29] op_sel_hi:[1,0]
	v_lshlrev_b32_e32 v68, 16, v254
	v_and_b32_e32 v69, 0xffff0000, v254
	v_pk_mul_f32 v[64:65], v[64:65], s[28:29] op_sel_hi:[1,0]
	v_pk_fma_f32 v[138:139], v[66:67], 0.5, v[70:71] op_sel_hi:[1,0,1]
	v_lshlrev_b32_e32 v66, 16, v253
	v_and_b32_e32 v67, 0xffff0000, v253
	v_pk_fma_f32 v[60:61], v[60:61], 0.5, v[64:65] op_sel_hi:[1,0,1]
	v_pk_mul_f32 v[64:65], v[68:69], s[28:29] op_sel_hi:[1,0]
	v_lshlrev_b32_e32 v70, 16, v255
	v_and_b32_e32 v71, 0xffff0000, v255
	v_pk_mul_f32 v[66:67], v[66:67], s[28:29] op_sel_hi:[1,0]
	v_pk_fma_f32 v[56:57], v[56:57], 0.5, v[64:65] op_sel_hi:[1,0,1]
	v_add_u32_e32 v64, s6, v148
	v_pk_fma_f32 v[62:63], v[62:63], 0.5, v[66:67] op_sel_hi:[1,0,1]
	v_pk_mul_f32 v[66:67], v[70:71], s[28:29] op_sel_hi:[1,0]
	v_ashrrev_i32_e32 v65, 31, v64
	v_pk_fma_f32 v[58:59], v[58:59], 0.5, v[66:67] op_sel_hi:[1,0,1]
	v_lshlrev_b64 v[64:65], 2, v[64:65]
	v_lshl_add_u64 v[68:69], s[20:21], 0, v[64:65]
	v_lshl_add_u64 v[76:77], s[22:23], 0, v[64:65]
	global_load_dwordx4 v[144:147], v[68:69], off offset:16
	global_load_dwordx4 v[152:155], v[68:69], off
	global_load_dwordx4 v[148:151], v[76:77], off offset:16
	global_load_dwordx4 v[156:159], v[76:77], off
	global_load_dwordx4 v[64:67], v[68:69], off offset:528
	global_load_dwordx4 v[72:75], v[68:69], off offset:512
	s_nop 0
	global_load_dwordx4 v[68:71], v[76:77], off offset:528
	s_nop 0
	global_load_dwordx4 v[76:79], v[76:77], off offset:512
	v_pk_add_f32 v[188:189], v[92:93], v[88:89]
	v_pk_add_f32 v[190:191], v[14:15], v[10:11]
	v_pk_add_f32 v[192:193], v[12:13], v[8:9]
	v_pk_add_f32 v[174:175], v[174:175], v[190:191]
	v_pk_add_f32 v[188:189], v[188:189], v[192:193]
	v_add_f32_e32 v174, v174, v175
	v_add_f32_e32 v188, v188, v189
	v_add_f32_e32 v174, v188, v174
	v_mov_b32_e32 v175, v174
	s_nop 1
	v_permlane16_swap_b32_e32 v174, v175
	v_add_f32_e32 v174, v174, v175
	v_mov_b32_e32 v175, v174
	s_nop 1
	v_permlane32_swap_b32_e32 v174, v175
	v_add_f32_e32 v174, v174, v175
	v_fmamk_f32 v193, v174, 0xbc800000, v89
	v_fmamk_f32 v192, v174, 0xbc800000, v88
	v_fmamk_f32 v195, v174, 0xbc800000, v91
	v_fmamk_f32 v194, v174, 0xbc800000, v90
	v_fmamk_f32 v189, v174, 0xbc800000, v95
	v_fmamk_f32 v188, v174, 0xbc800000, v94
	v_fmamk_f32 v191, v174, 0xbc800000, v93
	v_fmamk_f32 v190, v174, 0xbc800000, v92
	v_fmamk_f32 v201, v174, 0xbc800000, v9
	v_fmamk_f32 v200, v174, 0xbc800000, v8
	v_fmamk_f32 v203, v174, 0xbc800000, v11
	v_fmamk_f32 v202, v174, 0xbc800000, v10
	v_pk_mul_f32 v[194:195], v[194:195], v[194:195]
	v_pk_mul_f32 v[192:193], v[192:193], v[192:193]
	v_fmamk_f32 v197, v174, 0xbc800000, v15
	v_fmamk_f32 v196, v174, 0xbc800000, v14
	v_fmamk_f32 v199, v174, 0xbc800000, v13
	v_fmamk_f32 v198, v174, 0xbc800000, v12
	v_pk_fma_f32 v[190:191], v[190:191], v[190:191], v[192:193]
	v_pk_fma_f32 v[188:189], v[188:189], v[188:189], v[194:195]
	v_pk_mul_f32 v[192:193], v[202:203], v[202:203]
	v_pk_mul_f32 v[194:195], v[200:201], v[200:201]
	v_pk_fma_f32 v[192:193], v[196:197], v[196:197], v[192:193]
	v_pk_fma_f32 v[194:195], v[198:199], v[198:199], v[194:195]
	v_pk_add_f32 v[188:189], v[188:189], v[192:193]
	v_pk_add_f32 v[190:191], v[190:191], v[194:195]
	v_add_f32_e32 v188, v188, v189
	v_add_f32_e32 v175, v190, v191
	v_add_f32_e32 v175, v175, v188
	v_mov_b32_e32 v188, v175
	s_nop 1
	v_permlane16_swap_b32_e32 v175, v188
	s_lshl_b32 s6, s8, 3
	v_add_f32_e32 v175, v175, v188
	s_add_i32 s11, s6, 0
	v_mov_b32_e32 v188, v175
	s_add_i32 s11, s11, 0x21000
	s_nop 0
	v_permlane32_swap_b32_e32 v175, v188
	s_and_saveexec_b64 s[6:7], vcc
	s_cbranch_execz .LBB0_1711
	s_lshl_b32 s15, s9, 11
	s_add_i32 s15, s11, s15
	v_mul_f32_e32 v174, 0x3c800000, v174
	v_lshl_add_u32 v189, v186, 5, s15
	v_add_f32_e32 v175, v175, v188
	ds_write_b64 v189, v[174:175]

.LBB0_1903:
	v_mov_b32_e32 v187, v178
	s_mov_b32 s8, s68
	v_mov_b32_e32 v186, v177
	s_mov_b32 s9, s55
	s_lshl_b32 s7, s14, 2
	s_ashr_i32 s10, s8, 1
	s_lshl_b32 s31, s9, 6
	s_add_i32 s38, s10, s7
	s_lshl_b32 s10, s40, 8
	s_lshl_b32 s6, s8, 5
	s_ashr_i32 s39, s38, 31
	s_add_i32 s51, s31, s10
	v_add_u32_e32 v128, s51, v186
	s_and_b32 s7, s6, 32
	s_lshl_b64 s[38:39], s[38:39], 22
	v_ashrrev_i32_e32 v129, 31, v128
	s_add_u32 s38, s58, s38
	v_lshlrev_b64 v[128:129], 7, v[128:129]
	s_addc_u32 s39, s59, s39
	v_lshlrev_b32_e32 v148, 3, v187
	v_lshl_add_u64 v[128:129], s[38:39], 0, v[128:129]
	s_lshl_b32 s12, s7, 1
	v_ashrrev_i32_e32 v149, 31, v148
	v_lshl_add_u64 v[128:129], v[128:129], 0, s[12:13]
	v_lshl_add_u64 v[128:129], v[148:149], 1, v[128:129]
	v_add_co_u32_e32 v146, vcc, s71, v128
	global_load_dwordx4 v[130:133], v[128:129], off
	global_load_dwordx4 v[134:137], v[128:129], off offset:2048
	v_addc_co_u32_e32 v147, vcc, 0, v129, vcc
	v_add_co_u32_e32 v142, vcc, s69, v128
	global_load_dwordx4 v[138:141], v[146:147], off offset:-4096
	s_nop 0
	v_addc_co_u32_e32 v143, vcc, 0, v129, vcc
	global_load_dwordx4 v[142:145], v[142:143], off offset:2048
	v_add_co_u32_e32 v158, vcc, s70, v128
	global_load_dwordx4 v[154:157], v[146:147], off
	s_nop 0
	v_addc_co_u32_e32 v159, vcc, 0, v129, vcc
	global_load_dwordx4 v[150:153], v[158:159], off
	global_load_dwordx4 v[188:191], v[158:159], off offset:2048
	global_load_dwordx4 v[192:195], v[146:147], off offset:2048
	v_pk_mul_f32 v[90:91], v[90:91], 0.5 op_sel_hi:[1,0]
	v_pk_mul_f32 v[88:89], v[88:89], 0.5 op_sel_hi:[1,0]
	v_pk_mul_f32 v[174:175], v[86:87], 0.5 op_sel_hi:[1,0]
	v_pk_mul_f32 v[196:197], v[84:85], 0.5 op_sel_hi:[1,0]
	v_pk_mul_f32 v[198:199], v[82:83], 0.5 op_sel_hi:[1,0]
	v_pk_mul_f32 v[200:201], v[80:81], 0.5 op_sel_hi:[1,0]
	v_pk_mul_f32 v[14:15], v[14:15], 0.5 op_sel_hi:[1,0]
	v_pk_mul_f32 v[12:13], v[12:13], 0.5 op_sel_hi:[1,0]
	v_pk_mul_f32 v[94:95], v[94:95], 0.5 op_sel_hi:[1,0]
	v_pk_mul_f32 v[92:93], v[92:93], 0.5 op_sel_hi:[1,0]
	v_pk_mul_f32 v[10:11], v[10:11], 0.5 op_sel_hi:[1,0]
	v_pk_mul_f32 v[8:9], v[8:9], 0.5 op_sel_hi:[1,0]
	s_lshl_b32 s7, s14, 8
	s_add_i32 s6, s6, s7
	s_mov_b32 s101, 0
	s_mov_b32 s100, s33
	v_lshl_add_u64 v[242:243], v[128:129], 0, s[100:101]
	s_mov_b32 s100, s88
	v_lshl_add_u64 v[252:253], v[128:129], 0, s[100:101]
	s_mov_b32 s100, s3
	v_lshl_add_u64 v[230:231], v[128:129], 0, s[100:101]
	s_mov_b32 s100, s56
	v_lshl_add_u64 v[234:235], v[128:129], 0, s[100:101]
	global_load_dwordx4 v[222:225], v[242:243], off offset:-4096
	global_load_dwordx4 v[226:229], v[252:253], off offset:-4096
	global_load_dwordx4 v[230:233], v[230:231], off offset:2048
	global_load_dwordx4 v[234:237], v[234:235], off offset:2048
	global_load_dwordx4 v[238:241], v[242:243], off
	global_load_dwordx4 v[242:245], v[242:243], off offset:2048
	global_load_dwordx4 v[246:249], v[252:253], off
	global_load_dwordx4 v[252:255], v[252:253], off offset:2048
	s_waitcnt vmcnt(8)
	v_lshlrev_b32_e32 v80, 16, v130
	v_and_b32_e32 v81, 0xffff0000, v130
	v_lshlrev_b32_e32 v82, 16, v131
	v_and_b32_e32 v83, 0xffff0000, v131
	v_lshlrev_b32_e32 v84, 16, v132
	v_and_b32_e32 v85, 0xffff0000, v132
	v_lshlrev_b32_e32 v86, 16, v133
	v_and_b32_e32 v87, 0xffff0000, v133
	v_lshlrev_b32_e32 v130, 16, v134
	v_and_b32_e32 v131, 0xffff0000, v134
	v_lshlrev_b32_e32 v132, 16, v135
	v_and_b32_e32 v133, 0xffff0000, v135
	v_lshlrev_b32_e32 v134, 16, v136
	v_and_b32_e32 v135, 0xffff0000, v136
	v_lshlrev_b32_e32 v136, 16, v137
	v_and_b32_e32 v137, 0xffff0000, v137
	v_pk_fma_f32 v[90:91], v[86:87], s[28:29], v[90:91] op_sel_hi:[1,0,1]
	v_pk_fma_f32 v[88:89], v[84:85], s[28:29], v[88:89] op_sel_hi:[1,0,1]
	v_pk_fma_f32 v[86:87], v[132:133], s[28:29], v[14:15] op_sel_hi:[1,0,1]
	v_pk_fma_f32 v[84:85], v[130:131], s[28:29], v[12:13] op_sel_hi:[1,0,1]
	v_lshlrev_b32_e32 v130, 16, v142
	v_and_b32_e32 v131, 0xffff0000, v142
	v_lshlrev_b32_e32 v132, 16, v143
	v_and_b32_e32 v133, 0xffff0000, v143
	v_pk_fma_f32 v[94:95], v[82:83], s[28:29], v[94:95] op_sel_hi:[1,0,1]
	v_pk_fma_f32 v[92:93], v[80:81], s[28:29], v[92:93] op_sel_hi:[1,0,1]
	v_pk_fma_f32 v[82:83], v[136:137], s[28:29], v[10:11] op_sel_hi:[1,0,1]
	v_pk_fma_f32 v[80:81], v[134:135], s[28:29], v[8:9] op_sel_hi:[1,0,1]
	v_lshlrev_b32_e32 v134, 16, v144
	v_and_b32_e32 v135, 0xffff0000, v144
	v_lshlrev_b32_e32 v136, 16, v145
	v_and_b32_e32 v137, 0xffff0000, v145
	v_pk_mul_f32 v[130:131], v[130:131], s[28:29] op_sel_hi:[1,0]
	v_pk_mul_f32 v[132:133], v[132:133], s[28:29] op_sel_hi:[1,0]
	v_pk_fma_f32 v[4:5], v[4:5], 0.5, v[130:131] op_sel_hi:[1,0,1]
	v_pk_fma_f32 v[6:7], v[6:7], 0.5, v[132:133] op_sel_hi:[1,0,1]
	v_pk_mul_f32 v[130:131], v[134:135], s[28:29] op_sel_hi:[1,0]
	v_pk_mul_f32 v[132:133], v[136:137], s[28:29] op_sel_hi:[1,0]
	v_pk_fma_f32 v[0:1], v[0:1], 0.5, v[130:131] op_sel_hi:[1,0,1]
	v_pk_fma_f32 v[2:3], v[2:3], 0.5, v[132:133] op_sel_hi:[1,0,1]
	v_lshlrev_b32_e32 v130, 16, v150
	v_and_b32_e32 v131, 0xffff0000, v150
	v_lshlrev_b32_e32 v132, 16, v151
	v_and_b32_e32 v133, 0xffff0000, v151
	v_lshlrev_b32_e32 v134, 16, v152
	v_and_b32_e32 v135, 0xffff0000, v152
	v_lshlrev_b32_e32 v136, 16, v153
	v_and_b32_e32 v137, 0xffff0000, v153
	v_pk_mul_f32 v[130:131], v[130:131], s[28:29] op_sel_hi:[1,0]
	v_pk_mul_f32 v[132:133], v[132:133], s[28:29] op_sel_hi:[1,0]
	v_pk_fma_f32 v[100:101], v[100:101], 0.5, v[130:131] op_sel_hi:[1,0,1]
	v_pk_fma_f32 v[102:103], v[102:103], 0.5, v[132:133] op_sel_hi:[1,0,1]
	v_pk_mul_f32 v[130:131], v[134:135], s[28:29] op_sel_hi:[1,0]
	v_pk_mul_f32 v[132:133], v[136:137], s[28:29] op_sel_hi:[1,0]
	v_pk_fma_f32 v[96:97], v[96:97], 0.5, v[130:131] op_sel_hi:[1,0,1]
	v_pk_fma_f32 v[98:99], v[98:99], 0.5, v[132:133] op_sel_hi:[1,0,1]
	v_lshlrev_b32_e32 v130, 16, v154
	v_and_b32_e32 v131, 0xffff0000, v154
	v_lshlrev_b32_e32 v132, 16, v155
	v_and_b32_e32 v133, 0xffff0000, v155
	v_lshlrev_b32_e32 v134, 16, v156
	v_and_b32_e32 v135, 0xffff0000, v156
	v_lshlrev_b32_e32 v136, 16, v157
	v_and_b32_e32 v137, 0xffff0000, v157
	v_pk_mul_f32 v[130:131], v[130:131], s[28:29] op_sel_hi:[1,0]
	v_pk_mul_f32 v[132:133], v[132:133], s[28:29] op_sel_hi:[1,0]
	v_pk_fma_f32 v[20:21], v[20:21], 0.5, v[130:131] op_sel_hi:[1,0,1]
	v_pk_fma_f32 v[22:23], v[22:23], 0.5, v[132:133] op_sel_hi:[1,0,1]
	v_pk_mul_f32 v[130:131], v[134:135], s[28:29] op_sel_hi:[1,0]
	v_pk_mul_f32 v[132:133], v[136:137], s[28:29] op_sel_hi:[1,0]
	v_pk_fma_f32 v[16:17], v[16:17], 0.5, v[130:131] op_sel_hi:[1,0,1]
	v_pk_fma_f32 v[18:19], v[18:19], 0.5, v[132:133] op_sel_hi:[1,0,1]
	v_lshlrev_b32_e32 v130, 16, v188
	v_and_b32_e32 v131, 0xffff0000, v188
	v_lshlrev_b32_e32 v132, 16, v189
	v_and_b32_e32 v133, 0xffff0000, v189
	v_lshlrev_b32_e32 v134, 16, v190
	v_and_b32_e32 v135, 0xffff0000, v190
	v_lshlrev_b32_e32 v136, 16, v191
	v_and_b32_e32 v137, 0xffff0000, v191
	v_pk_mul_f32 v[130:131], v[130:131], s[28:29] op_sel_hi:[1,0]
	v_pk_mul_f32 v[132:133], v[132:133], s[28:29] op_sel_hi:[1,0]
	v_pk_fma_f32 v[108:109], v[108:109], 0.5, v[130:131] op_sel_hi:[1,0,1]
	v_pk_fma_f32 v[110:111], v[110:111], 0.5, v[132:133] op_sel_hi:[1,0,1]
	v_pk_mul_f32 v[130:131], v[134:135], s[28:29] op_sel_hi:[1,0]
	v_pk_mul_f32 v[132:133], v[136:137], s[28:29] op_sel_hi:[1,0]
	v_pk_fma_f32 v[104:105], v[104:105], 0.5, v[130:131] op_sel_hi:[1,0,1]
	v_pk_fma_f32 v[106:107], v[106:107], 0.5, v[132:133] op_sel_hi:[1,0,1]
	v_lshlrev_b32_e32 v130, 16, v192
	v_and_b32_e32 v131, 0xffff0000, v192
	v_lshlrev_b32_e32 v132, 16, v193
	v_and_b32_e32 v133, 0xffff0000, v193
	v_lshlrev_b32_e32 v134, 16, v194
	v_and_b32_e32 v135, 0xffff0000, v194
	v_lshlrev_b32_e32 v136, 16, v195
	v_and_b32_e32 v137, 0xffff0000, v195
	v_pk_mul_f32 v[130:131], v[130:131], s[28:29] op_sel_hi:[1,0]
	v_pk_mul_f32 v[132:133], v[132:133], s[28:29] op_sel_hi:[1,0]
	v_lshlrev_b32_e32 v146, 16, v138
	v_and_b32_e32 v147, 0xffff0000, v138
	v_lshlrev_b32_e32 v138, 16, v139
	v_and_b32_e32 v139, 0xffff0000, v139
	v_lshlrev_b32_e32 v158, 16, v140
	v_and_b32_e32 v159, 0xffff0000, v140
	v_lshlrev_b32_e32 v140, 16, v141
	v_and_b32_e32 v141, 0xffff0000, v141
	v_pk_fma_f32 v[30:31], v[30:31], 0.5, v[132:133] op_sel_hi:[1,0,1]
	v_pk_fma_f32 v[28:29], v[28:29], 0.5, v[130:131] op_sel_hi:[1,0,1]
	v_pk_mul_f32 v[130:131], v[134:135], s[28:29] op_sel_hi:[1,0]
	v_pk_mul_f32 v[132:133], v[136:137], s[28:29] op_sel_hi:[1,0]
	v_pk_fma_f32 v[14:15], v[138:139], s[28:29], v[174:175] op_sel_hi:[1,0,1]
	v_pk_fma_f32 v[12:13], v[146:147], s[28:29], v[196:197] op_sel_hi:[1,0,1]
	v_pk_fma_f32 v[10:11], v[140:141], s[28:29], v[198:199] op_sel_hi:[1,0,1]
	v_pk_fma_f32 v[8:9], v[158:159], s[28:29], v[200:201] op_sel_hi:[1,0,1]
	v_pk_fma_f32 v[26:27], v[26:27], 0.5, v[132:133] op_sel_hi:[1,0,1]
	v_pk_fma_f32 v[24:25], v[24:25], 0.5, v[130:131] op_sel_hi:[1,0,1]
	v_add_co_u32_e32 v142, vcc, s33, v128
	s_nop 1
	v_addc_co_u32_e32 v143, vcc, 0, v129, vcc
	v_add_co_u32_e32 v144, vcc, s88, v128
	v_pk_add_f32 v[174:175], v[94:95], v[90:91]
	s_nop 0
	v_addc_co_u32_e32 v145, vcc, 0, v129, vcc
	v_add_co_u32_e32 v138, vcc, s3, v128
	s_nop 1
	v_addc_co_u32_e32 v139, vcc, 0, v129, vcc
	v_add_co_u32_e32 v128, vcc, s56, v128
	s_nop 1
	v_addc_co_u32_e32 v129, vcc, 0, v129, vcc
	s_nop 0
	v_cmp_eq_u32_e32 vcc, 0, v187
	s_waitcnt vmcnt(7)
	v_lshlrev_b32_e32 v128, 16, v222
	v_and_b32_e32 v129, 0xffff0000, v222
	v_lshlrev_b32_e32 v142, 16, v224
	v_and_b32_e32 v143, 0xffff0000, v224
	v_pk_mul_f32 v[128:129], v[128:129], s[28:29] op_sel_hi:[1,0]
	v_lshlrev_b32_e32 v130, 16, v223
	v_and_b32_e32 v131, 0xffff0000, v223
	v_pk_fma_f32 v[116:117], v[116:117], 0.5, v[128:129] op_sel_hi:[1,0,1]
	v_pk_mul_f32 v[128:129], v[142:143], s[28:29] op_sel_hi:[1,0]
	v_lshlrev_b32_e32 v132, 16, v225
	v_and_b32_e32 v133, 0xffff0000, v225
	v_pk_mul_f32 v[130:131], v[130:131], s[28:29] op_sel_hi:[1,0]
	v_pk_fma_f32 v[112:113], v[112:113], 0.5, v[128:129] op_sel_hi:[1,0,1]
	s_waitcnt vmcnt(6)
	v_lshlrev_b32_e32 v128, 16, v226
	v_and_b32_e32 v129, 0xffff0000, v226
	v_pk_fma_f32 v[118:119], v[118:119], 0.5, v[130:131] op_sel_hi:[1,0,1]
	v_pk_mul_f32 v[130:131], v[132:133], s[28:29] op_sel_hi:[1,0]
	v_lshlrev_b32_e32 v132, 16, v228
	v_and_b32_e32 v133, 0xffff0000, v228
	v_pk_mul_f32 v[128:129], v[128:129], s[28:29] op_sel_hi:[1,0]
	v_pk_fma_f32 v[114:115], v[114:115], 0.5, v[130:131] op_sel_hi:[1,0,1]
	v_lshlrev_b32_e32 v130, 16, v227
	v_and_b32_e32 v131, 0xffff0000, v227
	v_pk_fma_f32 v[36:37], v[36:37], 0.5, v[128:129] op_sel_hi:[1,0,1]
	v_pk_mul_f32 v[128:129], v[132:133], s[28:29] op_sel_hi:[1,0]
	v_lshlrev_b32_e32 v134, 16, v229
	v_and_b32_e32 v135, 0xffff0000, v229
	v_pk_mul_f32 v[130:131], v[130:131], s[28:29] op_sel_hi:[1,0]
	v_pk_fma_f32 v[32:33], v[32:33], 0.5, v[128:129] op_sel_hi:[1,0,1]
	s_waitcnt vmcnt(5)
	v_lshlrev_b32_e32 v128, 16, v230
	v_and_b32_e32 v129, 0xffff0000, v230
	v_pk_fma_f32 v[38:39], v[38:39], 0.5, v[130:131] op_sel_hi:[1,0,1]
	v_pk_mul_f32 v[130:131], v[134:135], s[28:29] op_sel_hi:[1,0]
	v_lshlrev_b32_e32 v132, 16, v232
	v_and_b32_e32 v133, 0xffff0000, v232
	v_pk_mul_f32 v[128:129], v[128:129], s[28:29] op_sel_hi:[1,0]
	v_pk_fma_f32 v[34:35], v[34:35], 0.5, v[130:131] op_sel_hi:[1,0,1]
	v_lshlrev_b32_e32 v130, 16, v231
	v_and_b32_e32 v131, 0xffff0000, v231
	v_pk_fma_f32 v[124:125], v[124:125], 0.5, v[128:129] op_sel_hi:[1,0,1]
	v_pk_mul_f32 v[128:129], v[132:133], s[28:29] op_sel_hi:[1,0]
	v_lshlrev_b32_e32 v134, 16, v233
	v_and_b32_e32 v135, 0xffff0000, v233
	v_pk_mul_f32 v[130:131], v[130:131], s[28:29] op_sel_hi:[1,0]
	v_pk_fma_f32 v[120:121], v[120:121], 0.5, v[128:129] op_sel_hi:[1,0,1]
	s_waitcnt vmcnt(4)
	v_lshlrev_b32_e32 v128, 16, v234
	v_and_b32_e32 v129, 0xffff0000, v234
	v_pk_fma_f32 v[126:127], v[126:127], 0.5, v[130:131] op_sel_hi:[1,0,1]
	v_pk_mul_f32 v[130:131], v[134:135], s[28:29] op_sel_hi:[1,0]
	v_lshlrev_b32_e32 v132, 16, v236
	v_and_b32_e32 v133, 0xffff0000, v236
	v_pk_mul_f32 v[128:129], v[128:129], s[28:29] op_sel_hi:[1,0]
	v_pk_fma_f32 v[122:123], v[122:123], 0.5, v[130:131] op_sel_hi:[1,0,1]
	v_lshlrev_b32_e32 v130, 16, v235
	v_and_b32_e32 v131, 0xffff0000, v235
	v_pk_fma_f32 v[44:45], v[44:45], 0.5, v[128:129] op_sel_hi:[1,0,1]
	v_pk_mul_f32 v[128:129], v[132:133], s[28:29] op_sel_hi:[1,0]
	v_lshlrev_b32_e32 v134, 16, v237
	v_and_b32_e32 v135, 0xffff0000, v237
	v_pk_mul_f32 v[130:131], v[130:131], s[28:29] op_sel_hi:[1,0]
	v_pk_fma_f32 v[40:41], v[40:41], 0.5, v[128:129] op_sel_hi:[1,0,1]
	s_waitcnt vmcnt(3)
	v_lshlrev_b32_e32 v128, 16, v238
	v_and_b32_e32 v129, 0xffff0000, v238
	v_pk_fma_f32 v[46:47], v[46:47], 0.5, v[130:131] op_sel_hi:[1,0,1]
	v_pk_mul_f32 v[130:131], v[134:135], s[28:29] op_sel_hi:[1,0]
	v_lshlrev_b32_e32 v136, 16, v240
	v_and_b32_e32 v137, 0xffff0000, v240
	v_pk_mul_f32 v[128:129], v[128:129], s[28:29] op_sel_hi:[1,0]
	v_pk_fma_f32 v[42:43], v[42:43], 0.5, v[130:131] op_sel_hi:[1,0,1]
	v_lshlrev_b32_e32 v130, 16, v239
	v_and_b32_e32 v131, 0xffff0000, v239
	v_pk_fma_f32 v[132:133], v[76:77], 0.5, v[128:129] op_sel_hi:[1,0,1]
	v_pk_mul_f32 v[76:77], v[136:137], s[28:29] op_sel_hi:[1,0]
	v_lshlrev_b32_e32 v138, 16, v241
	v_and_b32_e32 v139, 0xffff0000, v241
	v_pk_mul_f32 v[130:131], v[130:131], s[28:29] op_sel_hi:[1,0]
	v_pk_fma_f32 v[128:129], v[72:73], 0.5, v[76:77] op_sel_hi:[1,0,1]
	s_waitcnt vmcnt(1)
	v_lshlrev_b32_e32 v72, 16, v246
	v_and_b32_e32 v73, 0xffff0000, v246
	v_pk_fma_f32 v[134:135], v[78:79], 0.5, v[130:131] op_sel_hi:[1,0,1]
	v_pk_mul_f32 v[78:79], v[138:139], s[28:29] op_sel_hi:[1,0]
	v_lshlrev_b32_e32 v76, 16, v248
	v_and_b32_e32 v77, 0xffff0000, v248
	v_pk_mul_f32 v[72:73], v[72:73], s[28:29] op_sel_hi:[1,0]
	v_pk_fma_f32 v[130:131], v[74:75], 0.5, v[78:79] op_sel_hi:[1,0,1]
	v_lshlrev_b32_e32 v74, 16, v247
	v_and_b32_e32 v75, 0xffff0000, v247
	v_pk_fma_f32 v[52:53], v[52:53], 0.5, v[72:73] op_sel_hi:[1,0,1]
	v_pk_mul_f32 v[72:73], v[76:77], s[28:29] op_sel_hi:[1,0]
	v_lshlrev_b32_e32 v78, 16, v249
	v_and_b32_e32 v79, 0xffff0000, v249
	v_pk_mul_f32 v[74:75], v[74:75], s[28:29] op_sel_hi:[1,0]
	v_pk_fma_f32 v[48:49], v[48:49], 0.5, v[72:73] op_sel_hi:[1,0,1]
	v_lshlrev_b32_e32 v72, 16, v242
	v_and_b32_e32 v73, 0xffff0000, v242
	v_pk_fma_f32 v[54:55], v[54:55], 0.5, v[74:75] op_sel_hi:[1,0,1]
	v_pk_mul_f32 v[74:75], v[78:79], s[28:29] op_sel_hi:[1,0]
	v_lshlrev_b32_e32 v76, 16, v244
	v_and_b32_e32 v77, 0xffff0000, v244
	v_pk_mul_f32 v[72:73], v[72:73], s[28:29] op_sel_hi:[1,0]
	v_pk_fma_f32 v[50:51], v[50:51], 0.5, v[74:75] op_sel_hi:[1,0,1]
	v_lshlrev_b32_e32 v74, 16, v243
	v_and_b32_e32 v75, 0xffff0000, v243
	v_pk_fma_f32 v[140:141], v[68:69], 0.5, v[72:73] op_sel_hi:[1,0,1]
	v_pk_mul_f32 v[68:69], v[76:77], s[28:29] op_sel_hi:[1,0]
	v_lshlrev_b32_e32 v78, 16, v245
	v_and_b32_e32 v79, 0xffff0000, v245
	v_pk_mul_f32 v[74:75], v[74:75], s[28:29] op_sel_hi:[1,0]
	v_pk_fma_f32 v[136:137], v[64:65], 0.5, v[68:69] op_sel_hi:[1,0,1]
	s_waitcnt vmcnt(0)
	v_lshlrev_b32_e32 v64, 16, v252
	v_and_b32_e32 v65, 0xffff0000, v252
	v_pk_fma_f32 v[142:143], v[70:71], 0.5, v[74:75] op_sel_hi:[1,0,1]
	v_pk_mul_f32 v[70:71], v[78:79], s[28:29] op_sel_hi:[1,0]
	v_lshlrev_b32_e32 v68, 16, v254
	v_and_b32_e32 v69, 0xffff0000, v254
	v_pk_mul_f32 v[64:65], v[64:65], s[28:29] op_sel_hi:[1,0]
	v_pk_fma_f32 v[138:139], v[66:67], 0.5, v[70:71] op_sel_hi:[1,0,1]
	v_lshlrev_b32_e32 v66, 16, v253
	v_and_b32_e32 v67, 0xffff0000, v253
	v_pk_fma_f32 v[60:61], v[60:61], 0.5, v[64:65] op_sel_hi:[1,0,1]
	v_pk_mul_f32 v[64:65], v[68:69], s[28:29] op_sel_hi:[1,0]
	v_lshlrev_b32_e32 v70, 16, v255
	v_and_b32_e32 v71, 0xffff0000, v255
	v_pk_mul_f32 v[66:67], v[66:67], s[28:29] op_sel_hi:[1,0]
	v_pk_fma_f32 v[56:57], v[56:57], 0.5, v[64:65] op_sel_hi:[1,0,1]
	v_add_u32_e32 v64, s6, v148
	v_pk_fma_f32 v[62:63], v[62:63], 0.5, v[66:67] op_sel_hi:[1,0,1]
	v_pk_mul_f32 v[66:67], v[70:71], s[28:29] op_sel_hi:[1,0]
	v_ashrrev_i32_e32 v65, 31, v64
	v_pk_fma_f32 v[58:59], v[58:59], 0.5, v[66:67] op_sel_hi:[1,0,1]
	v_lshlrev_b64 v[64:65], 2, v[64:65]
	v_lshl_add_u64 v[68:69], s[20:21], 0, v[64:65]
	v_lshl_add_u64 v[76:77], s[22:23], 0, v[64:65]
	global_load_dwordx4 v[144:147], v[68:69], off offset:16
	global_load_dwordx4 v[152:155], v[68:69], off
	global_load_dwordx4 v[148:151], v[76:77], off offset:16
	global_load_dwordx4 v[156:159], v[76:77], off
	global_load_dwordx4 v[64:67], v[68:69], off offset:528
	global_load_dwordx4 v[72:75], v[68:69], off offset:512
	s_nop 0
	global_load_dwordx4 v[68:71], v[76:77], off offset:528
	s_nop 0
	global_load_dwordx4 v[76:79], v[76:77], off offset:512
	v_pk_add_f32 v[188:189], v[92:93], v[88:89]
	v_pk_add_f32 v[190:191], v[14:15], v[10:11]
	v_pk_add_f32 v[192:193], v[12:13], v[8:9]
	v_pk_add_f32 v[174:175], v[174:175], v[190:191]
	v_pk_add_f32 v[188:189], v[188:189], v[192:193]
	v_add_f32_e32 v174, v174, v175
	v_add_f32_e32 v188, v188, v189
	v_add_f32_e32 v174, v188, v174
	v_mov_b32_e32 v175, v174
	s_nop 1
	v_permlane16_swap_b32_e32 v174, v175
	v_add_f32_e32 v174, v174, v175
	v_mov_b32_e32 v175, v174
	s_nop 1
	v_permlane32_swap_b32_e32 v174, v175
	v_add_f32_e32 v174, v174, v175
	v_fmamk_f32 v193, v174, 0xbc800000, v89
	v_fmamk_f32 v192, v174, 0xbc800000, v88
	v_fmamk_f32 v195, v174, 0xbc800000, v91
	v_fmamk_f32 v194, v174, 0xbc800000, v90
	v_fmamk_f32 v189, v174, 0xbc800000, v95
	v_fmamk_f32 v188, v174, 0xbc800000, v94
	v_fmamk_f32 v191, v174, 0xbc800000, v93
	v_fmamk_f32 v190, v174, 0xbc800000, v92
	v_fmamk_f32 v201, v174, 0xbc800000, v9
	v_fmamk_f32 v200, v174, 0xbc800000, v8
	v_fmamk_f32 v203, v174, 0xbc800000, v11
	v_fmamk_f32 v202, v174, 0xbc800000, v10
	v_pk_mul_f32 v[194:195], v[194:195], v[194:195]
	v_pk_mul_f32 v[192:193], v[192:193], v[192:193]
	v_fmamk_f32 v197, v174, 0xbc800000, v15
	v_fmamk_f32 v196, v174, 0xbc800000, v14
	v_fmamk_f32 v199, v174, 0xbc800000, v13
	v_fmamk_f32 v198, v174, 0xbc800000, v12
	v_pk_fma_f32 v[190:191], v[190:191], v[190:191], v[192:193]
	v_pk_fma_f32 v[188:189], v[188:189], v[188:189], v[194:195]
	v_pk_mul_f32 v[192:193], v[202:203], v[202:203]
	v_pk_mul_f32 v[194:195], v[200:201], v[200:201]
	v_pk_fma_f32 v[192:193], v[196:197], v[196:197], v[192:193]
	v_pk_fma_f32 v[194:195], v[198:199], v[198:199], v[194:195]
	v_pk_add_f32 v[188:189], v[188:189], v[192:193]
	v_pk_add_f32 v[190:191], v[190:191], v[194:195]
	v_add_f32_e32 v188, v188, v189
	v_add_f32_e32 v175, v190, v191
	v_add_f32_e32 v175, v175, v188
	v_mov_b32_e32 v188, v175
	s_nop 1
	v_permlane16_swap_b32_e32 v175, v188
	s_lshl_b32 s6, s8, 3
	v_add_f32_e32 v175, v175, v188
	s_add_i32 s11, s6, 0
	v_mov_b32_e32 v188, v175
	s_add_i32 s11, s11, 0x21000
	s_nop 0
	v_permlane32_swap_b32_e32 v175, v188
	s_and_saveexec_b64 s[6:7], vcc
	s_cbranch_execz .LBB0_1905
	s_lshl_b32 s15, s9, 11
	s_add_i32 s15, s11, s15
	v_mul_f32_e32 v174, 0x3c800000, v174
	v_lshl_add_u32 v189, v186, 5, s15
	v_add_f32_e32 v175, v175, v188
	ds_write_b64 v189, v[174:175]

.LBB0_2545:
	v_mov_b32_e32 v186, v177
	s_mov_b32 s6, s4
	v_mov_b32_e32 v187, v178
	s_mov_b32 s7, s54
	s_lshl_b32 s1, s12, 2
	s_ashr_i32 s8, s7, 1
	s_lshl_b32 s29, s6, 6
	s_add_i32 s36, s8, s1
	s_lshl_b32 s8, s38, 8
	s_lshl_b32 s0, s7, 5
	s_ashr_i32 s37, s36, 31
	s_add_i32 s75, s29, s8
	v_add_u32_e32 v128, s75, v186
	s_and_b32 s1, s0, 32
	s_lshl_b64 s[36:37], s[36:37], 22
	v_ashrrev_i32_e32 v129, 31, v128
	s_add_u32 s36, s58, s36
	v_lshlrev_b64 v[128:129], 7, v[128:129]
	s_addc_u32 s37, s59, s37
	v_lshlrev_b32_e32 v144, 3, v187
	v_lshl_add_u64 v[128:129], s[36:37], 0, v[128:129]
	s_lshl_b32 s10, s1, 1
	v_ashrrev_i32_e32 v145, 31, v144
	v_lshl_add_u64 v[128:129], v[128:129], 0, s[10:11]
	v_lshl_add_u64 v[132:133], v[144:145], 1, v[128:129]
	v_add_co_u32_e32 v128, vcc, s68, v132
	global_load_dwordx4 v[134:137], v[132:133], off
	global_load_dwordx4 v[138:141], v[132:133], off offset:2048
	v_addc_co_u32_e32 v129, vcc, 0, v133, vcc
	v_add_co_u32_e32 v130, vcc, s66, v132
	global_load_dwordx4 v[146:149], v[128:129], off offset:-4096
	s_nop 0
	v_addc_co_u32_e32 v131, vcc, 0, v133, vcc
	global_load_dwordx4 v[150:153], v[130:131], off offset:2048
	v_add_co_u32_e32 v130, vcc, s67, v132
	s_lshl_b32 s1, s12, 8
	s_nop 0
	v_addc_co_u32_e32 v131, vcc, 0, v133, vcc
	global_load_dwordx4 v[154:157], v[130:131], off
	global_load_dwordx4 v[188:191], v[128:129], off
	global_load_dwordx4 v[192:195], v[130:131], off offset:2048
	s_nop 0
	global_load_dwordx4 v[128:131], v[128:129], off offset:2048
	s_add_i32 s0, s0, s1
	s_mov_b32 s101, 0
	s_mov_b32 s100, s70
	v_lshl_add_u64 v[246:247], v[132:133], 0, s[100:101]
	s_mov_b32 s100, s71
	v_lshl_add_u64 v[252:253], v[132:133], 0, s[100:101]
	s_mov_b32 s100, s51
	v_lshl_add_u64 v[230:231], v[132:133], 0, s[100:101]
	s_mov_b32 s100, s69
	v_lshl_add_u64 v[234:235], v[132:133], 0, s[100:101]
	global_load_dwordx4 v[222:225], v[246:247], off offset:-4096
	global_load_dwordx4 v[226:229], v[252:253], off offset:-4096
	global_load_dwordx4 v[230:233], v[230:231], off offset:2048
	global_load_dwordx4 v[234:237], v[234:235], off offset:2048
	global_load_dwordx4 v[238:241], v[246:247], off
	global_load_dwordx4 v[242:245], v[252:253], off
	global_load_dwordx4 v[246:249], v[246:247], off offset:2048
	global_load_dwordx4 v[252:255], v[252:253], off offset:2048
	s_waitcnt vmcnt(8)
	v_lshlrev_b32_e32 v142, 16, v134
	v_and_b32_e32 v143, 0xffff0000, v134
	v_lshlrev_b32_e32 v134, 16, v135
	v_and_b32_e32 v135, 0xffff0000, v135
	v_lshlrev_b32_e32 v158, 16, v136
	v_and_b32_e32 v159, 0xffff0000, v136
	v_lshlrev_b32_e32 v136, 16, v137
	v_and_b32_e32 v137, 0xffff0000, v137
	v_lshlrev_b32_e32 v174, 16, v138
	v_and_b32_e32 v175, 0xffff0000, v138
	v_lshlrev_b32_e32 v138, 16, v139
	v_and_b32_e32 v139, 0xffff0000, v139
	v_lshlrev_b32_e32 v196, 16, v140
	v_and_b32_e32 v197, 0xffff0000, v140
	v_lshlrev_b32_e32 v140, 16, v141
	v_and_b32_e32 v141, 0xffff0000, v141
	v_pk_fma_f32 v[106:107], v[134:135], s[26:27], v[106:107] op_sel_hi:[1,0,1]
	v_pk_fma_f32 v[98:99], v[136:137], s[26:27], v[98:99] op_sel_hi:[1,0,1]
	v_lshlrev_b32_e32 v134, 16, v146
	v_and_b32_e32 v135, 0xffff0000, v146
	v_lshlrev_b32_e32 v136, 16, v147
	v_and_b32_e32 v137, 0xffff0000, v147
	v_pk_fma_f32 v[86:87], v[138:139], s[26:27], v[86:87] op_sel_hi:[1,0,1]
	v_pk_fma_f32 v[82:83], v[140:141], s[26:27], v[82:83] op_sel_hi:[1,0,1]
	v_lshlrev_b32_e32 v138, 16, v150
	v_and_b32_e32 v139, 0xffff0000, v150
	v_lshlrev_b32_e32 v140, 16, v151
	v_and_b32_e32 v141, 0xffff0000, v151
	v_pk_fma_f32 v[30:31], v[136:137], s[26:27], v[30:31] op_sel_hi:[1,0,1]
	v_pk_fma_f32 v[28:29], v[134:135], s[26:27], v[28:29] op_sel_hi:[1,0,1]
	v_lshlrev_b32_e32 v134, 16, v154
	v_and_b32_e32 v135, 0xffff0000, v154
	v_lshlrev_b32_e32 v136, 16, v155
	v_and_b32_e32 v137, 0xffff0000, v155
	v_pk_fma_f32 v[104:105], v[142:143], s[26:27], v[104:105] op_sel_hi:[1,0,1]
	v_lshlrev_b32_e32 v142, 16, v148
	v_and_b32_e32 v143, 0xffff0000, v148
	v_pk_fma_f32 v[6:7], v[140:141], s[26:27], v[6:7] op_sel_hi:[1,0,1]
	v_pk_fma_f32 v[4:5], v[138:139], s[26:27], v[4:5] op_sel_hi:[1,0,1]
	v_lshlrev_b32_e32 v138, 16, v156
	v_and_b32_e32 v139, 0xffff0000, v156
	v_lshlrev_b32_e32 v140, 16, v157
	v_and_b32_e32 v141, 0xffff0000, v157
	v_pk_fma_f32 v[94:95], v[136:137], s[26:27], v[94:95] op_sel_hi:[1,0,1]
	v_pk_fma_f32 v[92:93], v[134:135], s[26:27], v[92:93] op_sel_hi:[1,0,1]
	v_lshlrev_b32_e32 v134, 16, v188
	v_and_b32_e32 v135, 0xffff0000, v188
	v_lshlrev_b32_e32 v136, 16, v189
	v_and_b32_e32 v137, 0xffff0000, v189
	v_pk_fma_f32 v[16:17], v[142:143], s[26:27], v[16:17] op_sel_hi:[1,0,1]
	v_pk_fma_f32 v[90:91], v[140:141], s[26:27], v[90:91] op_sel_hi:[1,0,1]
	v_pk_fma_f32 v[88:89], v[138:139], s[26:27], v[88:89] op_sel_hi:[1,0,1]
	v_lshlrev_b32_e32 v138, 16, v190
	v_and_b32_e32 v139, 0xffff0000, v190
	v_lshlrev_b32_e32 v140, 16, v191
	v_and_b32_e32 v141, 0xffff0000, v191
	v_pk_fma_f32 v[14:15], v[136:137], s[26:27], v[14:15] op_sel_hi:[1,0,1]
	v_pk_fma_f32 v[12:13], v[134:135], s[26:27], v[12:13] op_sel_hi:[1,0,1]
	v_lshlrev_b32_e32 v134, 16, v192
	v_and_b32_e32 v135, 0xffff0000, v192
	v_lshlrev_b32_e32 v136, 16, v193
	v_and_b32_e32 v137, 0xffff0000, v193
	v_add_co_u32_e32 v142, vcc, s70, v132
	v_lshlrev_b32_e32 v146, 16, v149
	v_and_b32_e32 v147, 0xffff0000, v149
	v_lshlrev_b32_e32 v148, 16, v152
	v_and_b32_e32 v149, 0xffff0000, v152
	v_lshlrev_b32_e32 v150, 16, v153
	v_and_b32_e32 v151, 0xffff0000, v153
	v_pk_fma_f32 v[10:11], v[140:141], s[26:27], v[10:11] op_sel_hi:[1,0,1]
	v_pk_fma_f32 v[8:9], v[138:139], s[26:27], v[8:9] op_sel_hi:[1,0,1]
	v_lshlrev_b32_e32 v138, 16, v194
	v_and_b32_e32 v139, 0xffff0000, v194
	v_lshlrev_b32_e32 v140, 16, v195
	v_and_b32_e32 v141, 0xffff0000, v195
	v_pk_fma_f32 v[110:111], v[136:137], s[26:27], v[110:111] op_sel_hi:[1,0,1]
	v_pk_fma_f32 v[108:109], v[134:135], s[26:27], v[108:109] op_sel_hi:[1,0,1]
	v_lshlrev_b32_e32 v134, 16, v128
	v_and_b32_e32 v135, 0xffff0000, v128
	v_lshlrev_b32_e32 v128, 16, v129
	v_and_b32_e32 v129, 0xffff0000, v129
	v_lshlrev_b32_e32 v136, 16, v130
	v_and_b32_e32 v137, 0xffff0000, v130
	v_lshlrev_b32_e32 v130, 16, v131
	v_and_b32_e32 v131, 0xffff0000, v131
	v_addc_co_u32_e32 v143, vcc, 0, v133, vcc
	v_pk_fma_f32 v[96:97], v[158:159], s[26:27], v[96:97] op_sel_hi:[1,0,1]
	v_pk_fma_f32 v[84:85], v[174:175], s[26:27], v[84:85] op_sel_hi:[1,0,1]
	v_pk_fma_f32 v[80:81], v[196:197], s[26:27], v[80:81] op_sel_hi:[1,0,1]
	v_pk_fma_f32 v[18:19], v[146:147], s[26:27], v[18:19] op_sel_hi:[1,0,1]
	v_pk_fma_f32 v[2:3], v[150:151], s[26:27], v[2:3] op_sel_hi:[1,0,1]
	v_pk_fma_f32 v[0:1], v[148:149], s[26:27], v[0:1] op_sel_hi:[1,0,1]
	v_pk_fma_f32 v[102:103], v[140:141], s[26:27], v[102:103] op_sel_hi:[1,0,1]
	v_pk_fma_f32 v[100:101], v[138:139], s[26:27], v[100:101] op_sel_hi:[1,0,1]
	v_pk_fma_f32 v[26:27], v[128:129], s[26:27], v[26:27] op_sel_hi:[1,0,1]
	v_pk_fma_f32 v[24:25], v[134:135], s[26:27], v[24:25] op_sel_hi:[1,0,1]
	v_pk_fma_f32 v[22:23], v[130:131], s[26:27], v[22:23] op_sel_hi:[1,0,1]
	v_pk_fma_f32 v[20:21], v[136:137], s[26:27], v[20:21] op_sel_hi:[1,0,1]
	v_add_co_u32_e32 v158, vcc, s71, v132
	s_nop 1
	v_addc_co_u32_e32 v159, vcc, 0, v133, vcc
	v_add_co_u32_e32 v138, vcc, s51, v132
	s_nop 0
	v_addc_co_u32_e32 v139, vcc, 0, v133, vcc
	v_add_co_u32_e32 v132, vcc, s69, v132
	v_pk_add_f32 v[174:175], v[106:107], v[98:99]
	s_nop 0
	v_addc_co_u32_e32 v133, vcc, 0, v133, vcc
	v_cmp_eq_u32_e32 vcc, 0, v187
	s_waitcnt vmcnt(7)
	v_lshlrev_b32_e32 v132, 16, v222
	v_and_b32_e32 v133, 0xffff0000, v222
	v_lshlrev_b32_e32 v128, 16, v223
	v_and_b32_e32 v129, 0xffff0000, v223
	v_pk_fma_f32 v[118:119], v[128:129], s[26:27], v[118:119] op_sel_hi:[1,0,1]
	s_waitcnt vmcnt(6)
	v_lshlrev_b32_e32 v128, 16, v226
	v_and_b32_e32 v129, 0xffff0000, v226
	v_lshlrev_b32_e32 v142, 16, v224
	v_and_b32_e32 v143, 0xffff0000, v224
	v_lshlrev_b32_e32 v130, 16, v225
	v_and_b32_e32 v131, 0xffff0000, v225
	v_pk_fma_f32 v[116:117], v[132:133], s[26:27], v[116:117] op_sel_hi:[1,0,1]
	v_lshlrev_b32_e32 v132, 16, v228
	v_and_b32_e32 v133, 0xffff0000, v228
	v_pk_fma_f32 v[36:37], v[128:129], s[26:27], v[36:37] op_sel_hi:[1,0,1]
	s_waitcnt vmcnt(5)
	v_lshlrev_b32_e32 v128, 16, v230
	v_and_b32_e32 v129, 0xffff0000, v230
	v_pk_fma_f32 v[114:115], v[130:131], s[26:27], v[114:115] op_sel_hi:[1,0,1]
	v_lshlrev_b32_e32 v130, 16, v227
	v_and_b32_e32 v131, 0xffff0000, v227
	v_pk_fma_f32 v[32:33], v[132:133], s[26:27], v[32:33] op_sel_hi:[1,0,1]
	v_lshlrev_b32_e32 v132, 16, v232
	v_and_b32_e32 v133, 0xffff0000, v232
	v_pk_fma_f32 v[124:125], v[128:129], s[26:27], v[124:125] op_sel_hi:[1,0,1]
	s_waitcnt vmcnt(4)
	v_lshlrev_b32_e32 v128, 16, v234
	v_and_b32_e32 v129, 0xffff0000, v234
	v_lshlrev_b32_e32 v134, 16, v229
	v_and_b32_e32 v135, 0xffff0000, v229
	v_pk_fma_f32 v[38:39], v[130:131], s[26:27], v[38:39] op_sel_hi:[1,0,1]
	v_lshlrev_b32_e32 v130, 16, v231
	v_and_b32_e32 v131, 0xffff0000, v231
	v_pk_fma_f32 v[120:121], v[132:133], s[26:27], v[120:121] op_sel_hi:[1,0,1]
	v_lshlrev_b32_e32 v132, 16, v236
	v_and_b32_e32 v133, 0xffff0000, v236
	v_pk_fma_f32 v[44:45], v[128:129], s[26:27], v[44:45] op_sel_hi:[1,0,1]
	s_waitcnt vmcnt(3)
	v_lshlrev_b32_e32 v128, 16, v238
	v_and_b32_e32 v129, 0xffff0000, v238
	v_pk_fma_f32 v[34:35], v[134:135], s[26:27], v[34:35] op_sel_hi:[1,0,1]
	v_lshlrev_b32_e32 v134, 16, v233
	v_and_b32_e32 v135, 0xffff0000, v233
	v_pk_fma_f32 v[126:127], v[130:131], s[26:27], v[126:127] op_sel_hi:[1,0,1]
	v_lshlrev_b32_e32 v130, 16, v235
	v_and_b32_e32 v131, 0xffff0000, v235
	v_pk_fma_f32 v[40:41], v[132:133], s[26:27], v[40:41] op_sel_hi:[1,0,1]
	v_pk_fma_f32 v[132:133], v[128:129], s[26:27], v[76:77] op_sel_hi:[1,0,1]
	s_waitcnt vmcnt(2)
	v_lshlrev_b32_e32 v76, 16, v244
	v_and_b32_e32 v77, 0xffff0000, v244
	v_pk_fma_f32 v[122:123], v[134:135], s[26:27], v[122:123] op_sel_hi:[1,0,1]
	v_lshlrev_b32_e32 v134, 16, v237
	v_and_b32_e32 v135, 0xffff0000, v237
	v_pk_fma_f32 v[46:47], v[130:131], s[26:27], v[46:47] op_sel_hi:[1,0,1]
	v_lshlrev_b32_e32 v130, 16, v239
	v_and_b32_e32 v131, 0xffff0000, v239
	v_lshlrev_b32_e32 v136, 16, v240
	v_and_b32_e32 v137, 0xffff0000, v240
	v_lshlrev_b32_e32 v138, 16, v241
	v_and_b32_e32 v139, 0xffff0000, v241
	v_pk_fma_f32 v[48:49], v[76:77], s[26:27], v[48:49] op_sel_hi:[1,0,1]
	s_waitcnt vmcnt(1)
	v_lshlrev_b32_e32 v76, 16, v248
	v_and_b32_e32 v77, 0xffff0000, v248
	v_pk_fma_f32 v[42:43], v[134:135], s[26:27], v[42:43] op_sel_hi:[1,0,1]
	v_pk_fma_f32 v[134:135], v[130:131], s[26:27], v[78:79] op_sel_hi:[1,0,1]
	v_pk_fma_f32 v[130:131], v[138:139], s[26:27], v[74:75] op_sel_hi:[1,0,1]
	v_pk_fma_f32 v[128:129], v[136:137], s[26:27], v[72:73] op_sel_hi:[1,0,1]
	v_lshlrev_b32_e32 v72, 16, v242
	v_and_b32_e32 v73, 0xffff0000, v242
	v_lshlrev_b32_e32 v74, 16, v243
	v_and_b32_e32 v75, 0xffff0000, v243
	v_lshlrev_b32_e32 v78, 16, v245
	v_and_b32_e32 v79, 0xffff0000, v245
	v_pk_fma_f32 v[136:137], v[76:77], s[26:27], v[64:65] op_sel_hi:[1,0,1]
	s_waitcnt vmcnt(0)
	v_lshlrev_b32_e32 v64, 16, v252
	v_and_b32_e32 v65, 0xffff0000, v252
	v_pk_fma_f32 v[54:55], v[74:75], s[26:27], v[54:55] op_sel_hi:[1,0,1]
	v_pk_fma_f32 v[52:53], v[72:73], s[26:27], v[52:53] op_sel_hi:[1,0,1]
	v_pk_fma_f32 v[50:51], v[78:79], s[26:27], v[50:51] op_sel_hi:[1,0,1]
	v_lshlrev_b32_e32 v72, 16, v246
	v_and_b32_e32 v73, 0xffff0000, v246
	v_lshlrev_b32_e32 v74, 16, v247
	v_and_b32_e32 v75, 0xffff0000, v247
	v_lshlrev_b32_e32 v78, 16, v249
	v_and_b32_e32 v79, 0xffff0000, v249
	v_pk_fma_f32 v[60:61], v[64:65], s[26:27], v[60:61] op_sel_hi:[1,0,1]
	v_add_u32_e32 v64, s0, v144
	v_pk_fma_f32 v[112:113], v[142:143], s[26:27], v[112:113] op_sel_hi:[1,0,1]
	v_pk_fma_f32 v[142:143], v[74:75], s[26:27], v[70:71] op_sel_hi:[1,0,1]
	v_pk_fma_f32 v[140:141], v[72:73], s[26:27], v[68:69] op_sel_hi:[1,0,1]
	v_pk_fma_f32 v[138:139], v[78:79], s[26:27], v[66:67] op_sel_hi:[1,0,1]
	v_lshlrev_b32_e32 v66, 16, v253
	v_and_b32_e32 v67, 0xffff0000, v253
	v_lshlrev_b32_e32 v68, 16, v254
	v_and_b32_e32 v69, 0xffff0000, v254
	v_lshlrev_b32_e32 v70, 16, v255
	v_and_b32_e32 v71, 0xffff0000, v255
	v_ashrrev_i32_e32 v65, 31, v64
	v_pk_fma_f32 v[62:63], v[66:67], s[26:27], v[62:63] op_sel_hi:[1,0,1]
	v_pk_fma_f32 v[58:59], v[70:71], s[26:27], v[58:59] op_sel_hi:[1,0,1]
	v_pk_fma_f32 v[56:57], v[68:69], s[26:27], v[56:57] op_sel_hi:[1,0,1]
	v_lshlrev_b64 v[64:65], 2, v[64:65]
	v_lshl_add_u64 v[68:69], s[18:19], 0, v[64:65]
	v_lshl_add_u64 v[76:77], s[20:21], 0, v[64:65]
	global_load_dwordx4 v[144:147], v[68:69], off offset:16
	global_load_dwordx4 v[152:155], v[68:69], off
	global_load_dwordx4 v[148:151], v[76:77], off offset:16
	global_load_dwordx4 v[156:159], v[76:77], off
	global_load_dwordx4 v[64:67], v[68:69], off offset:528
	global_load_dwordx4 v[72:75], v[68:69], off offset:512
	s_nop 0
	global_load_dwordx4 v[68:71], v[76:77], off offset:528
	s_nop 0
	global_load_dwordx4 v[76:79], v[76:77], off offset:512
	v_pk_add_f32 v[188:189], v[104:105], v[96:97]
	v_pk_add_f32 v[190:191], v[30:31], v[18:19]
	v_pk_add_f32 v[192:193], v[28:29], v[16:17]
	v_pk_add_f32 v[174:175], v[174:175], v[190:191]
	v_pk_add_f32 v[188:189], v[188:189], v[192:193]
	v_add_f32_e32 v174, v174, v175
	v_add_f32_e32 v188, v188, v189
	v_add_f32_e32 v174, v188, v174
	v_mov_b32_e32 v175, v174
	s_nop 1
	v_permlane16_swap_b32_e32 v174, v175
	v_add_f32_e32 v174, v174, v175
	v_mov_b32_e32 v175, v174
	s_nop 1
	v_permlane32_swap_b32_e32 v174, v175
	v_add_f32_e32 v174, v174, v175
	v_fmamk_f32 v193, v174, 0xbc800000, v97
	v_fmamk_f32 v192, v174, 0xbc800000, v96
	v_fmamk_f32 v195, v174, 0xbc800000, v99
	v_fmamk_f32 v194, v174, 0xbc800000, v98
	v_fmamk_f32 v189, v174, 0xbc800000, v107
	v_fmamk_f32 v188, v174, 0xbc800000, v106
	v_fmamk_f32 v191, v174, 0xbc800000, v105
	v_fmamk_f32 v190, v174, 0xbc800000, v104
	v_fmamk_f32 v201, v174, 0xbc800000, v17
	v_fmamk_f32 v200, v174, 0xbc800000, v16
	v_fmamk_f32 v203, v174, 0xbc800000, v19
	v_fmamk_f32 v202, v174, 0xbc800000, v18
	v_pk_mul_f32 v[194:195], v[194:195], v[194:195]
	v_pk_mul_f32 v[192:193], v[192:193], v[192:193]
	v_fmamk_f32 v197, v174, 0xbc800000, v31
	v_fmamk_f32 v196, v174, 0xbc800000, v30
	v_fmamk_f32 v199, v174, 0xbc800000, v29
	v_fmamk_f32 v198, v174, 0xbc800000, v28
	v_pk_fma_f32 v[190:191], v[190:191], v[190:191], v[192:193]
	v_pk_fma_f32 v[188:189], v[188:189], v[188:189], v[194:195]
	v_pk_mul_f32 v[192:193], v[202:203], v[202:203]
	v_pk_mul_f32 v[194:195], v[200:201], v[200:201]
	v_pk_fma_f32 v[192:193], v[196:197], v[196:197], v[192:193]
	v_pk_fma_f32 v[194:195], v[198:199], v[198:199], v[194:195]
	v_pk_add_f32 v[188:189], v[188:189], v[192:193]
	v_pk_add_f32 v[190:191], v[190:191], v[194:195]
	v_add_f32_e32 v188, v188, v189
	v_add_f32_e32 v175, v190, v191
	v_add_f32_e32 v175, v175, v188
	v_mov_b32_e32 v188, v175
	s_nop 1
	v_permlane16_swap_b32_e32 v175, v188
	s_lshl_b32 s0, s7, 3
	v_add_f32_e32 v175, v175, v188
	s_add_i32 s9, s0, 0
	v_mov_b32_e32 v188, v175
	s_add_i32 s9, s9, 0x21000
	s_nop 0
	v_permlane32_swap_b32_e32 v175, v188
	s_and_saveexec_b64 s[0:1], vcc
	s_cbranch_execz .LBB0_2547
	s_lshl_b32 s13, s6, 11
	s_add_i32 s13, s9, s13
	v_mul_f32_e32 v174, 0x3c800000, v174
	v_add_f32_e32 v175, v175, v188
	v_lshl_add_u32 v188, v186, 5, s13
	ds_write_b64 v188, v[174:175]

.LBB0_2775:
	v_mov_b32_e32 v187, v178
	s_mov_b32 s6, s53
	v_mov_b32_e32 v186, v177
	s_mov_b32 s7, s2
	s_lshl_b32 s1, s12, 2
	s_ashr_i32 s8, s6, 1
	s_lshl_b32 s27, s7, 6
	s_add_i32 s36, s8, s1
	s_lshl_b32 s8, s38, 8
	s_lshl_b32 s0, s6, 5
	s_ashr_i32 s37, s36, 31
	s_add_i32 s29, s27, s8
	v_add_u32_e32 v128, s29, v186
	s_and_b32 s1, s0, 32
	s_lshl_b64 s[36:37], s[36:37], 22
	v_ashrrev_i32_e32 v129, 31, v128
	s_add_u32 s36, s58, s36
	v_lshlrev_b64 v[128:129], 7, v[128:129]
	s_addc_u32 s37, s59, s37
	v_lshlrev_b32_e32 v144, 3, v187
	v_lshl_add_u64 v[128:129], s[36:37], 0, v[128:129]
	s_lshl_b32 s10, s1, 1
	v_ashrrev_i32_e32 v145, 31, v144
	v_lshl_add_u64 v[128:129], v[128:129], 0, s[10:11]
	v_lshl_add_u64 v[132:133], v[144:145], 1, v[128:129]
	v_add_co_u32_e32 v128, vcc, s65, v132
	global_load_dwordx4 v[134:137], v[132:133], off
	global_load_dwordx4 v[138:141], v[132:133], off offset:2048
	v_addc_co_u32_e32 v129, vcc, 0, v133, vcc
	v_add_co_u32_e32 v130, vcc, s56, v132
	global_load_dwordx4 v[146:149], v[128:129], off offset:-4096
	s_nop 0
	v_addc_co_u32_e32 v131, vcc, 0, v133, vcc
	global_load_dwordx4 v[150:153], v[130:131], off offset:2048
	v_add_co_u32_e32 v130, vcc, s64, v132
	s_lshl_b32 s1, s12, 8
	s_nop 0
	v_addc_co_u32_e32 v131, vcc, 0, v133, vcc
	global_load_dwordx4 v[154:157], v[130:131], off
	global_load_dwordx4 v[188:191], v[128:129], off
	global_load_dwordx4 v[192:195], v[130:131], off offset:2048
	s_nop 0
	global_load_dwordx4 v[128:131], v[128:129], off offset:2048
	s_add_i32 s0, s0, s1
	s_mov_b32 s101, 0
	s_mov_b32 s100, s67
	v_lshl_add_u64 v[246:247], v[132:133], 0, s[100:101]
	s_mov_b32 s100, s68
	v_lshl_add_u64 v[252:253], v[132:133], 0, s[100:101]
	s_mov_b32 s100, s50
	v_lshl_add_u64 v[230:231], v[132:133], 0, s[100:101]
	s_mov_b32 s100, s66
	v_lshl_add_u64 v[234:235], v[132:133], 0, s[100:101]
	global_load_dwordx4 v[222:225], v[246:247], off offset:-4096
	global_load_dwordx4 v[226:229], v[252:253], off offset:-4096
	global_load_dwordx4 v[230:233], v[230:231], off offset:2048
	global_load_dwordx4 v[234:237], v[234:235], off offset:2048
	global_load_dwordx4 v[238:241], v[246:247], off
	global_load_dwordx4 v[242:245], v[252:253], off
	global_load_dwordx4 v[246:249], v[246:247], off offset:2048
	global_load_dwordx4 v[252:255], v[252:253], off offset:2048
	s_waitcnt vmcnt(8)
	v_lshlrev_b32_e32 v142, 16, v134
	v_and_b32_e32 v143, 0xffff0000, v134
	v_lshlrev_b32_e32 v134, 16, v135
	v_and_b32_e32 v135, 0xffff0000, v135
	v_lshlrev_b32_e32 v158, 16, v136
	v_and_b32_e32 v159, 0xffff0000, v136
	v_lshlrev_b32_e32 v136, 16, v137
	v_and_b32_e32 v137, 0xffff0000, v137
	v_lshlrev_b32_e32 v174, 16, v138
	v_and_b32_e32 v175, 0xffff0000, v138
	v_lshlrev_b32_e32 v138, 16, v139
	v_and_b32_e32 v139, 0xffff0000, v139
	v_lshlrev_b32_e32 v196, 16, v140
	v_and_b32_e32 v197, 0xffff0000, v140
	v_lshlrev_b32_e32 v140, 16, v141
	v_and_b32_e32 v141, 0xffff0000, v141
	v_pk_fma_f32 v[106:107], v[134:135], s[24:25], v[106:107] op_sel_hi:[1,0,1]
	v_pk_fma_f32 v[98:99], v[136:137], s[24:25], v[98:99] op_sel_hi:[1,0,1]
	v_lshlrev_b32_e32 v134, 16, v146
	v_and_b32_e32 v135, 0xffff0000, v146
	v_lshlrev_b32_e32 v136, 16, v147
	v_and_b32_e32 v137, 0xffff0000, v147
	v_pk_fma_f32 v[86:87], v[138:139], s[24:25], v[86:87] op_sel_hi:[1,0,1]
	v_pk_fma_f32 v[82:83], v[140:141], s[24:25], v[82:83] op_sel_hi:[1,0,1]
	v_lshlrev_b32_e32 v138, 16, v150
	v_and_b32_e32 v139, 0xffff0000, v150
	v_lshlrev_b32_e32 v140, 16, v151
	v_and_b32_e32 v141, 0xffff0000, v151
	v_pk_fma_f32 v[30:31], v[136:137], s[24:25], v[30:31] op_sel_hi:[1,0,1]
	v_pk_fma_f32 v[28:29], v[134:135], s[24:25], v[28:29] op_sel_hi:[1,0,1]
	v_lshlrev_b32_e32 v134, 16, v154
	v_and_b32_e32 v135, 0xffff0000, v154
	v_lshlrev_b32_e32 v136, 16, v155
	v_and_b32_e32 v137, 0xffff0000, v155
	v_pk_fma_f32 v[104:105], v[142:143], s[24:25], v[104:105] op_sel_hi:[1,0,1]
	v_lshlrev_b32_e32 v142, 16, v148
	v_and_b32_e32 v143, 0xffff0000, v148
	v_pk_fma_f32 v[6:7], v[140:141], s[24:25], v[6:7] op_sel_hi:[1,0,1]
	v_pk_fma_f32 v[4:5], v[138:139], s[24:25], v[4:5] op_sel_hi:[1,0,1]
	v_lshlrev_b32_e32 v138, 16, v156
	v_and_b32_e32 v139, 0xffff0000, v156
	v_lshlrev_b32_e32 v140, 16, v157
	v_and_b32_e32 v141, 0xffff0000, v157
	v_pk_fma_f32 v[94:95], v[136:137], s[24:25], v[94:95] op_sel_hi:[1,0,1]
	v_pk_fma_f32 v[92:93], v[134:135], s[24:25], v[92:93] op_sel_hi:[1,0,1]
	v_lshlrev_b32_e32 v134, 16, v188
	v_and_b32_e32 v135, 0xffff0000, v188
	v_lshlrev_b32_e32 v136, 16, v189
	v_and_b32_e32 v137, 0xffff0000, v189
	v_pk_fma_f32 v[16:17], v[142:143], s[24:25], v[16:17] op_sel_hi:[1,0,1]
	v_pk_fma_f32 v[90:91], v[140:141], s[24:25], v[90:91] op_sel_hi:[1,0,1]
	v_pk_fma_f32 v[88:89], v[138:139], s[24:25], v[88:89] op_sel_hi:[1,0,1]
	v_lshlrev_b32_e32 v138, 16, v190
	v_and_b32_e32 v139, 0xffff0000, v190
	v_lshlrev_b32_e32 v140, 16, v191
	v_and_b32_e32 v141, 0xffff0000, v191
	v_pk_fma_f32 v[14:15], v[136:137], s[24:25], v[14:15] op_sel_hi:[1,0,1]
	v_pk_fma_f32 v[12:13], v[134:135], s[24:25], v[12:13] op_sel_hi:[1,0,1]
	v_lshlrev_b32_e32 v134, 16, v192
	v_and_b32_e32 v135, 0xffff0000, v192
	v_lshlrev_b32_e32 v136, 16, v193
	v_and_b32_e32 v137, 0xffff0000, v193
	v_add_co_u32_e32 v142, vcc, s67, v132
	v_lshlrev_b32_e32 v146, 16, v149
	v_and_b32_e32 v147, 0xffff0000, v149
	v_lshlrev_b32_e32 v148, 16, v152
	v_and_b32_e32 v149, 0xffff0000, v152
	v_lshlrev_b32_e32 v150, 16, v153
	v_and_b32_e32 v151, 0xffff0000, v153
	v_pk_fma_f32 v[10:11], v[140:141], s[24:25], v[10:11] op_sel_hi:[1,0,1]
	v_pk_fma_f32 v[8:9], v[138:139], s[24:25], v[8:9] op_sel_hi:[1,0,1]
	v_lshlrev_b32_e32 v138, 16, v194
	v_and_b32_e32 v139, 0xffff0000, v194
	v_lshlrev_b32_e32 v140, 16, v195
	v_and_b32_e32 v141, 0xffff0000, v195
	v_pk_fma_f32 v[110:111], v[136:137], s[24:25], v[110:111] op_sel_hi:[1,0,1]
	v_pk_fma_f32 v[108:109], v[134:135], s[24:25], v[108:109] op_sel_hi:[1,0,1]
	v_lshlrev_b32_e32 v134, 16, v128
	v_and_b32_e32 v135, 0xffff0000, v128
	v_lshlrev_b32_e32 v128, 16, v129
	v_and_b32_e32 v129, 0xffff0000, v129
	v_lshlrev_b32_e32 v136, 16, v130
	v_and_b32_e32 v137, 0xffff0000, v130
	v_lshlrev_b32_e32 v130, 16, v131
	v_and_b32_e32 v131, 0xffff0000, v131
	v_addc_co_u32_e32 v143, vcc, 0, v133, vcc
	v_pk_fma_f32 v[96:97], v[158:159], s[24:25], v[96:97] op_sel_hi:[1,0,1]
	v_pk_fma_f32 v[84:85], v[174:175], s[24:25], v[84:85] op_sel_hi:[1,0,1]
	v_pk_fma_f32 v[80:81], v[196:197], s[24:25], v[80:81] op_sel_hi:[1,0,1]
	v_pk_fma_f32 v[18:19], v[146:147], s[24:25], v[18:19] op_sel_hi:[1,0,1]
	v_pk_fma_f32 v[2:3], v[150:151], s[24:25], v[2:3] op_sel_hi:[1,0,1]
	v_pk_fma_f32 v[0:1], v[148:149], s[24:25], v[0:1] op_sel_hi:[1,0,1]
	v_pk_fma_f32 v[102:103], v[140:141], s[24:25], v[102:103] op_sel_hi:[1,0,1]
	v_pk_fma_f32 v[100:101], v[138:139], s[24:25], v[100:101] op_sel_hi:[1,0,1]
	v_pk_fma_f32 v[26:27], v[128:129], s[24:25], v[26:27] op_sel_hi:[1,0,1]
	v_pk_fma_f32 v[24:25], v[134:135], s[24:25], v[24:25] op_sel_hi:[1,0,1]
	v_pk_fma_f32 v[22:23], v[130:131], s[24:25], v[22:23] op_sel_hi:[1,0,1]
	v_pk_fma_f32 v[20:21], v[136:137], s[24:25], v[20:21] op_sel_hi:[1,0,1]
	v_add_co_u32_e32 v158, vcc, s68, v132
	s_nop 1
	v_addc_co_u32_e32 v159, vcc, 0, v133, vcc
	v_add_co_u32_e32 v138, vcc, s50, v132
	s_nop 0
	v_addc_co_u32_e32 v139, vcc, 0, v133, vcc
	v_add_co_u32_e32 v132, vcc, s66, v132
	v_pk_add_f32 v[174:175], v[106:107], v[98:99]
	s_nop 0
	v_addc_co_u32_e32 v133, vcc, 0, v133, vcc
	v_cmp_eq_u32_e32 vcc, 0, v187
	s_waitcnt vmcnt(7)
	v_lshlrev_b32_e32 v132, 16, v222
	v_and_b32_e32 v133, 0xffff0000, v222
	v_lshlrev_b32_e32 v128, 16, v223
	v_and_b32_e32 v129, 0xffff0000, v223
	v_pk_fma_f32 v[118:119], v[128:129], s[24:25], v[118:119] op_sel_hi:[1,0,1]
	s_waitcnt vmcnt(6)
	v_lshlrev_b32_e32 v128, 16, v226
	v_and_b32_e32 v129, 0xffff0000, v226
	v_lshlrev_b32_e32 v142, 16, v224
	v_and_b32_e32 v143, 0xffff0000, v224
	v_lshlrev_b32_e32 v130, 16, v225
	v_and_b32_e32 v131, 0xffff0000, v225
	v_pk_fma_f32 v[116:117], v[132:133], s[24:25], v[116:117] op_sel_hi:[1,0,1]
	v_lshlrev_b32_e32 v132, 16, v228
	v_and_b32_e32 v133, 0xffff0000, v228
	v_pk_fma_f32 v[36:37], v[128:129], s[24:25], v[36:37] op_sel_hi:[1,0,1]
	s_waitcnt vmcnt(5)
	v_lshlrev_b32_e32 v128, 16, v230
	v_and_b32_e32 v129, 0xffff0000, v230
	v_pk_fma_f32 v[114:115], v[130:131], s[24:25], v[114:115] op_sel_hi:[1,0,1]
	v_lshlrev_b32_e32 v130, 16, v227
	v_and_b32_e32 v131, 0xffff0000, v227
	v_pk_fma_f32 v[32:33], v[132:133], s[24:25], v[32:33] op_sel_hi:[1,0,1]
	v_lshlrev_b32_e32 v132, 16, v232
	v_and_b32_e32 v133, 0xffff0000, v232
	v_pk_fma_f32 v[124:125], v[128:129], s[24:25], v[124:125] op_sel_hi:[1,0,1]
	s_waitcnt vmcnt(4)
	v_lshlrev_b32_e32 v128, 16, v234
	v_and_b32_e32 v129, 0xffff0000, v234
	v_lshlrev_b32_e32 v134, 16, v229
	v_and_b32_e32 v135, 0xffff0000, v229
	v_pk_fma_f32 v[38:39], v[130:131], s[24:25], v[38:39] op_sel_hi:[1,0,1]
	v_lshlrev_b32_e32 v130, 16, v231
	v_and_b32_e32 v131, 0xffff0000, v231
	v_pk_fma_f32 v[120:121], v[132:133], s[24:25], v[120:121] op_sel_hi:[1,0,1]
	v_lshlrev_b32_e32 v132, 16, v236
	v_and_b32_e32 v133, 0xffff0000, v236
	v_pk_fma_f32 v[44:45], v[128:129], s[24:25], v[44:45] op_sel_hi:[1,0,1]
	s_waitcnt vmcnt(3)
	v_lshlrev_b32_e32 v128, 16, v238
	v_and_b32_e32 v129, 0xffff0000, v238
	v_pk_fma_f32 v[34:35], v[134:135], s[24:25], v[34:35] op_sel_hi:[1,0,1]
	v_lshlrev_b32_e32 v134, 16, v233
	v_and_b32_e32 v135, 0xffff0000, v233
	v_pk_fma_f32 v[126:127], v[130:131], s[24:25], v[126:127] op_sel_hi:[1,0,1]
	v_lshlrev_b32_e32 v130, 16, v235
	v_and_b32_e32 v131, 0xffff0000, v235
	v_pk_fma_f32 v[40:41], v[132:133], s[24:25], v[40:41] op_sel_hi:[1,0,1]
	v_pk_fma_f32 v[132:133], v[128:129], s[24:25], v[76:77] op_sel_hi:[1,0,1]
	s_waitcnt vmcnt(2)
	v_lshlrev_b32_e32 v76, 16, v244
	v_and_b32_e32 v77, 0xffff0000, v244
	v_pk_fma_f32 v[122:123], v[134:135], s[24:25], v[122:123] op_sel_hi:[1,0,1]
	v_lshlrev_b32_e32 v134, 16, v237
	v_and_b32_e32 v135, 0xffff0000, v237
	v_pk_fma_f32 v[46:47], v[130:131], s[24:25], v[46:47] op_sel_hi:[1,0,1]
	v_lshlrev_b32_e32 v130, 16, v239
	v_and_b32_e32 v131, 0xffff0000, v239
	v_lshlrev_b32_e32 v136, 16, v240
	v_and_b32_e32 v137, 0xffff0000, v240
	v_lshlrev_b32_e32 v138, 16, v241
	v_and_b32_e32 v139, 0xffff0000, v241
	v_pk_fma_f32 v[48:49], v[76:77], s[24:25], v[48:49] op_sel_hi:[1,0,1]
	s_waitcnt vmcnt(1)
	v_lshlrev_b32_e32 v76, 16, v248
	v_and_b32_e32 v77, 0xffff0000, v248
	v_pk_fma_f32 v[42:43], v[134:135], s[24:25], v[42:43] op_sel_hi:[1,0,1]
	v_pk_fma_f32 v[134:135], v[130:131], s[24:25], v[78:79] op_sel_hi:[1,0,1]
	v_pk_fma_f32 v[130:131], v[138:139], s[24:25], v[74:75] op_sel_hi:[1,0,1]
	v_pk_fma_f32 v[128:129], v[136:137], s[24:25], v[72:73] op_sel_hi:[1,0,1]
	v_lshlrev_b32_e32 v72, 16, v242
	v_and_b32_e32 v73, 0xffff0000, v242
	v_lshlrev_b32_e32 v74, 16, v243
	v_and_b32_e32 v75, 0xffff0000, v243
	v_lshlrev_b32_e32 v78, 16, v245
	v_and_b32_e32 v79, 0xffff0000, v245
	v_pk_fma_f32 v[136:137], v[76:77], s[24:25], v[64:65] op_sel_hi:[1,0,1]
	s_waitcnt vmcnt(0)
	v_lshlrev_b32_e32 v64, 16, v252
	v_and_b32_e32 v65, 0xffff0000, v252
	v_pk_fma_f32 v[54:55], v[74:75], s[24:25], v[54:55] op_sel_hi:[1,0,1]
	v_pk_fma_f32 v[52:53], v[72:73], s[24:25], v[52:53] op_sel_hi:[1,0,1]
	v_pk_fma_f32 v[50:51], v[78:79], s[24:25], v[50:51] op_sel_hi:[1,0,1]
	v_lshlrev_b32_e32 v72, 16, v246
	v_and_b32_e32 v73, 0xffff0000, v246
	v_lshlrev_b32_e32 v74, 16, v247
	v_and_b32_e32 v75, 0xffff0000, v247
	v_lshlrev_b32_e32 v78, 16, v249
	v_and_b32_e32 v79, 0xffff0000, v249
	v_pk_fma_f32 v[60:61], v[64:65], s[24:25], v[60:61] op_sel_hi:[1,0,1]
	v_add_u32_e32 v64, s0, v144
	v_pk_fma_f32 v[112:113], v[142:143], s[24:25], v[112:113] op_sel_hi:[1,0,1]
	v_pk_fma_f32 v[142:143], v[74:75], s[24:25], v[70:71] op_sel_hi:[1,0,1]
	v_pk_fma_f32 v[140:141], v[72:73], s[24:25], v[68:69] op_sel_hi:[1,0,1]
	v_pk_fma_f32 v[138:139], v[78:79], s[24:25], v[66:67] op_sel_hi:[1,0,1]
	v_lshlrev_b32_e32 v66, 16, v253
	v_and_b32_e32 v67, 0xffff0000, v253
	v_lshlrev_b32_e32 v68, 16, v254
	v_and_b32_e32 v69, 0xffff0000, v254
	v_lshlrev_b32_e32 v70, 16, v255
	v_and_b32_e32 v71, 0xffff0000, v255
	v_ashrrev_i32_e32 v65, 31, v64
	v_pk_fma_f32 v[62:63], v[66:67], s[24:25], v[62:63] op_sel_hi:[1,0,1]
	v_pk_fma_f32 v[58:59], v[70:71], s[24:25], v[58:59] op_sel_hi:[1,0,1]
	v_pk_fma_f32 v[56:57], v[68:69], s[24:25], v[56:57] op_sel_hi:[1,0,1]
	v_lshlrev_b64 v[64:65], 2, v[64:65]
	v_lshl_add_u64 v[68:69], s[16:17], 0, v[64:65]
	v_lshl_add_u64 v[76:77], s[18:19], 0, v[64:65]
	global_load_dwordx4 v[144:147], v[68:69], off offset:16
	global_load_dwordx4 v[152:155], v[68:69], off
	global_load_dwordx4 v[148:151], v[76:77], off offset:16
	global_load_dwordx4 v[156:159], v[76:77], off
	global_load_dwordx4 v[64:67], v[68:69], off offset:528
	global_load_dwordx4 v[72:75], v[68:69], off offset:512
	s_nop 0
	global_load_dwordx4 v[68:71], v[76:77], off offset:528
	s_nop 0
	global_load_dwordx4 v[76:79], v[76:77], off offset:512
	v_pk_add_f32 v[188:189], v[104:105], v[96:97]
	v_pk_add_f32 v[190:191], v[30:31], v[18:19]
	v_pk_add_f32 v[192:193], v[28:29], v[16:17]
	v_pk_add_f32 v[174:175], v[174:175], v[190:191]
	v_pk_add_f32 v[188:189], v[188:189], v[192:193]
	v_add_f32_e32 v174, v174, v175
	v_add_f32_e32 v188, v188, v189
	v_add_f32_e32 v174, v188, v174
	v_mov_b32_e32 v175, v174
	s_nop 1
	v_permlane16_swap_b32_e32 v174, v175
	v_add_f32_e32 v174, v174, v175
	v_mov_b32_e32 v175, v174
	s_nop 1
	v_permlane32_swap_b32_e32 v174, v175
	v_add_f32_e32 v174, v174, v175
	v_fmamk_f32 v193, v174, 0xbc800000, v97
	v_fmamk_f32 v192, v174, 0xbc800000, v96
	v_fmamk_f32 v195, v174, 0xbc800000, v99
	v_fmamk_f32 v194, v174, 0xbc800000, v98
	v_fmamk_f32 v189, v174, 0xbc800000, v107
	v_fmamk_f32 v188, v174, 0xbc800000, v106
	v_fmamk_f32 v191, v174, 0xbc800000, v105
	v_fmamk_f32 v190, v174, 0xbc800000, v104
	v_fmamk_f32 v201, v174, 0xbc800000, v17
	v_fmamk_f32 v200, v174, 0xbc800000, v16
	v_fmamk_f32 v203, v174, 0xbc800000, v19
	v_fmamk_f32 v202, v174, 0xbc800000, v18
	v_pk_mul_f32 v[194:195], v[194:195], v[194:195]
	v_pk_mul_f32 v[192:193], v[192:193], v[192:193]
	v_fmamk_f32 v197, v174, 0xbc800000, v31
	v_fmamk_f32 v196, v174, 0xbc800000, v30
	v_fmamk_f32 v199, v174, 0xbc800000, v29
	v_fmamk_f32 v198, v174, 0xbc800000, v28
	v_pk_fma_f32 v[190:191], v[190:191], v[190:191], v[192:193]
	v_pk_fma_f32 v[188:189], v[188:189], v[188:189], v[194:195]
	v_pk_mul_f32 v[192:193], v[202:203], v[202:203]
	v_pk_mul_f32 v[194:195], v[200:201], v[200:201]
	v_pk_fma_f32 v[192:193], v[196:197], v[196:197], v[192:193]
	v_pk_fma_f32 v[194:195], v[198:199], v[198:199], v[194:195]
	v_pk_add_f32 v[188:189], v[188:189], v[192:193]
	v_pk_add_f32 v[190:191], v[190:191], v[194:195]
	v_add_f32_e32 v188, v188, v189
	v_add_f32_e32 v175, v190, v191
	v_add_f32_e32 v175, v175, v188
	v_mov_b32_e32 v188, v175
	s_nop 1
	v_permlane16_swap_b32_e32 v175, v188
	s_lshl_b32 s0, s6, 3
	v_add_f32_e32 v175, v175, v188
	s_add_i32 s9, s0, 0
	v_mov_b32_e32 v188, v175
	s_add_i32 s9, s9, 0x21000
	s_nop 0
	v_permlane32_swap_b32_e32 v175, v188
	s_and_saveexec_b64 s[0:1], vcc
	s_cbranch_execz .LBB0_2777
	s_lshl_b32 s13, s7, 11
	s_add_i32 s13, s9, s13
	v_mul_f32_e32 v174, 0x3c800000, v174
	v_add_f32_e32 v175, v175, v188
	v_lshl_add_u32 v188, v186, 5, s13
	ds_write_b64 v188, v[174:175]

.LBB0_2969:
	v_mov_b32_e32 v177, v183
	s_mov_b32 s2, s45
	v_mov_b32_e32 v176, v184
	s_mov_b32 s3, s66
	s_lshl_b32 s0, s8, 2
	s_ashr_i32 s1, s3, 1
	s_lshl_b32 s25, s2, 6
	s_add_i32 s0, s1, s0
	s_lshl_b32 s4, s31, 8
	s_ashr_i32 s1, s0, 31
	s_add_i32 s5, s25, s4
	s_lshl_b32 s34, s3, 5
	v_add_u32_e32 v128, s5, v177
	s_lshl_b64 s[0:1], s[0:1], 22
	v_ashrrev_i32_e32 v129, 31, v128
	s_add_u32 s0, s58, s0
	v_lshlrev_b64 v[128:129], 7, v[128:129]
	s_addc_u32 s1, s59, s1
	v_lshl_add_u64 v[128:129], s[0:1], 0, v[128:129]
	s_lshl_b32 s0, s3, 6
	v_lshlrev_b32_e32 v148, 3, v176
	s_and_b32 s6, s0, 64
	v_ashrrev_i32_e32 v149, 31, v148
	v_lshl_add_u64 v[128:129], v[128:129], 0, s[6:7]
	v_lshl_add_u64 v[128:129], v[148:149], 1, v[128:129]
	v_add_co_u32_e32 v146, vcc, s71, v128
	global_load_dwordx4 v[130:133], v[128:129], off
	global_load_dwordx4 v[134:137], v[128:129], off offset:2048
	v_addc_co_u32_e32 v147, vcc, 0, v129, vcc
	v_add_co_u32_e32 v142, vcc, s33, v128
	global_load_dwordx4 v[138:141], v[146:147], off offset:-4096
	s_nop 0
	v_addc_co_u32_e32 v143, vcc, 0, v129, vcc
	global_load_dwordx4 v[142:145], v[142:143], off offset:2048
	v_add_co_u32_e32 v158, vcc, s70, v128
	global_load_dwordx4 v[154:157], v[146:147], off
	s_nop 0
	v_addc_co_u32_e32 v159, vcc, 0, v129, vcc
	global_load_dwordx4 v[150:153], v[158:159], off
	global_load_dwordx4 v[178:181], v[158:159], off offset:2048
	global_load_dwordx4 v[192:195], v[146:147], off offset:2048
	v_pk_mul_f32 v[50:51], v[50:51], 0.5 op_sel_hi:[1,0]
	v_pk_mul_f32 v[48:49], v[48:49], 0.5 op_sel_hi:[1,0]
	v_pk_mul_f32 v[174:175], v[46:47], 0.5 op_sel_hi:[1,0]
	v_pk_mul_f32 v[196:197], v[44:45], 0.5 op_sel_hi:[1,0]
	v_pk_mul_f32 v[198:199], v[42:43], 0.5 op_sel_hi:[1,0]
	v_pk_mul_f32 v[200:201], v[40:41], 0.5 op_sel_hi:[1,0]
	v_pk_mul_f32 v[14:15], v[14:15], 0.5 op_sel_hi:[1,0]
	v_pk_mul_f32 v[12:13], v[12:13], 0.5 op_sel_hi:[1,0]
	v_pk_mul_f32 v[54:55], v[54:55], 0.5 op_sel_hi:[1,0]
	v_pk_mul_f32 v[52:53], v[52:53], 0.5 op_sel_hi:[1,0]
	v_pk_mul_f32 v[2:3], v[2:3], 0.5 op_sel_hi:[1,0]
	v_pk_mul_f32 v[0:1], v[0:1], 0.5 op_sel_hi:[1,0]
	s_lshl_b32 s0, s8, 8
	s_add_i32 s0, s34, s0
	s_mov_b32 s101, 0
	s_mov_b32 s100, s73
	v_lshl_add_u64 v[242:243], v[128:129], 0, s[100:101]
	s_mov_b32 s100, s74
	v_lshl_add_u64 v[252:253], v[128:129], 0, s[100:101]
	s_mov_b32 s100, s56
	v_lshl_add_u64 v[230:231], v[128:129], 0, s[100:101]
	s_mov_b32 s100, s72
	v_lshl_add_u64 v[234:235], v[128:129], 0, s[100:101]
	global_load_dwordx4 v[222:225], v[242:243], off offset:-4096
	global_load_dwordx4 v[226:229], v[252:253], off offset:-4096
	global_load_dwordx4 v[230:233], v[230:231], off offset:2048
	global_load_dwordx4 v[234:237], v[234:235], off offset:2048
	global_load_dwordx4 v[238:241], v[242:243], off
	global_load_dwordx4 v[242:245], v[242:243], off offset:2048
	global_load_dwordx4 v[246:249], v[252:253], off
	global_load_dwordx4 v[252:255], v[252:253], off offset:2048
	s_waitcnt vmcnt(8)
	v_lshlrev_b32_e32 v40, 16, v130
	v_and_b32_e32 v41, 0xffff0000, v130
	v_lshlrev_b32_e32 v42, 16, v131
	v_and_b32_e32 v43, 0xffff0000, v131
	v_lshlrev_b32_e32 v44, 16, v132
	v_and_b32_e32 v45, 0xffff0000, v132
	v_lshlrev_b32_e32 v46, 16, v133
	v_and_b32_e32 v47, 0xffff0000, v133
	v_lshlrev_b32_e32 v130, 16, v134
	v_and_b32_e32 v131, 0xffff0000, v134
	v_lshlrev_b32_e32 v132, 16, v135
	v_and_b32_e32 v133, 0xffff0000, v135
	v_lshlrev_b32_e32 v134, 16, v136
	v_and_b32_e32 v135, 0xffff0000, v136
	v_lshlrev_b32_e32 v136, 16, v137
	v_and_b32_e32 v137, 0xffff0000, v137
	v_pk_fma_f32 v[50:51], v[46:47], s[22:23], v[50:51] op_sel_hi:[1,0,1]
	v_pk_fma_f32 v[48:49], v[44:45], s[22:23], v[48:49] op_sel_hi:[1,0,1]
	v_pk_fma_f32 v[46:47], v[132:133], s[22:23], v[14:15] op_sel_hi:[1,0,1]
	v_pk_fma_f32 v[44:45], v[130:131], s[22:23], v[12:13] op_sel_hi:[1,0,1]
	v_lshlrev_b32_e32 v130, 16, v142
	v_and_b32_e32 v131, 0xffff0000, v142
	v_lshlrev_b32_e32 v132, 16, v143
	v_and_b32_e32 v133, 0xffff0000, v143
	v_pk_fma_f32 v[54:55], v[42:43], s[22:23], v[54:55] op_sel_hi:[1,0,1]
	v_pk_fma_f32 v[52:53], v[40:41], s[22:23], v[52:53] op_sel_hi:[1,0,1]
	v_pk_fma_f32 v[42:43], v[136:137], s[22:23], v[2:3] op_sel_hi:[1,0,1]
	v_pk_fma_f32 v[40:41], v[134:135], s[22:23], v[0:1] op_sel_hi:[1,0,1]
	v_lshlrev_b32_e32 v134, 16, v144
	v_and_b32_e32 v135, 0xffff0000, v144
	v_lshlrev_b32_e32 v136, 16, v145
	v_and_b32_e32 v137, 0xffff0000, v145
	v_pk_mul_f32 v[130:131], v[130:131], s[22:23] op_sel_hi:[1,0]
	v_pk_mul_f32 v[132:133], v[132:133], s[22:23] op_sel_hi:[1,0]
	v_pk_fma_f32 v[4:5], v[4:5], 0.5, v[130:131] op_sel_hi:[1,0,1]
	v_pk_fma_f32 v[6:7], v[6:7], 0.5, v[132:133] op_sel_hi:[1,0,1]
	v_pk_mul_f32 v[130:131], v[134:135], s[22:23] op_sel_hi:[1,0]
	v_pk_mul_f32 v[132:133], v[136:137], s[22:23] op_sel_hi:[1,0]
	v_pk_fma_f32 v[8:9], v[8:9], 0.5, v[130:131] op_sel_hi:[1,0,1]
	v_pk_fma_f32 v[10:11], v[10:11], 0.5, v[132:133] op_sel_hi:[1,0,1]
	v_lshlrev_b32_e32 v130, 16, v150
	v_and_b32_e32 v131, 0xffff0000, v150
	v_lshlrev_b32_e32 v132, 16, v151
	v_and_b32_e32 v133, 0xffff0000, v151
	v_lshlrev_b32_e32 v134, 16, v152
	v_and_b32_e32 v135, 0xffff0000, v152
	v_lshlrev_b32_e32 v136, 16, v153
	v_and_b32_e32 v137, 0xffff0000, v153
	v_pk_mul_f32 v[130:131], v[130:131], s[22:23] op_sel_hi:[1,0]
	v_pk_mul_f32 v[132:133], v[132:133], s[22:23] op_sel_hi:[1,0]
	v_pk_fma_f32 v[64:65], v[64:65], 0.5, v[130:131] op_sel_hi:[1,0,1]
	v_pk_fma_f32 v[66:67], v[66:67], 0.5, v[132:133] op_sel_hi:[1,0,1]
	v_pk_mul_f32 v[130:131], v[134:135], s[22:23] op_sel_hi:[1,0]
	v_pk_mul_f32 v[132:133], v[136:137], s[22:23] op_sel_hi:[1,0]
	v_pk_fma_f32 v[68:69], v[68:69], 0.5, v[130:131] op_sel_hi:[1,0,1]
	v_pk_fma_f32 v[70:71], v[70:71], 0.5, v[132:133] op_sel_hi:[1,0,1]
	v_lshlrev_b32_e32 v130, 16, v154
	v_and_b32_e32 v131, 0xffff0000, v154
	v_lshlrev_b32_e32 v132, 16, v155
	v_and_b32_e32 v133, 0xffff0000, v155
	v_lshlrev_b32_e32 v134, 16, v156
	v_and_b32_e32 v135, 0xffff0000, v156
	v_lshlrev_b32_e32 v136, 16, v157
	v_and_b32_e32 v137, 0xffff0000, v157
	v_pk_mul_f32 v[130:131], v[130:131], s[22:23] op_sel_hi:[1,0]
	v_pk_mul_f32 v[132:133], v[132:133], s[22:23] op_sel_hi:[1,0]
	v_pk_fma_f32 v[16:17], v[16:17], 0.5, v[130:131] op_sel_hi:[1,0,1]
	v_pk_fma_f32 v[18:19], v[18:19], 0.5, v[132:133] op_sel_hi:[1,0,1]
	v_pk_mul_f32 v[130:131], v[134:135], s[22:23] op_sel_hi:[1,0]
	v_pk_mul_f32 v[132:133], v[136:137], s[22:23] op_sel_hi:[1,0]
	v_pk_fma_f32 v[20:21], v[20:21], 0.5, v[130:131] op_sel_hi:[1,0,1]
	v_pk_fma_f32 v[22:23], v[22:23], 0.5, v[132:133] op_sel_hi:[1,0,1]
	v_lshlrev_b32_e32 v130, 16, v178
	v_and_b32_e32 v131, 0xffff0000, v178
	v_lshlrev_b32_e32 v132, 16, v179
	v_and_b32_e32 v133, 0xffff0000, v179
	v_lshlrev_b32_e32 v134, 16, v180
	v_and_b32_e32 v135, 0xffff0000, v180
	v_lshlrev_b32_e32 v136, 16, v181
	v_and_b32_e32 v137, 0xffff0000, v181
	v_pk_mul_f32 v[130:131], v[130:131], s[22:23] op_sel_hi:[1,0]
	v_pk_mul_f32 v[132:133], v[132:133], s[22:23] op_sel_hi:[1,0]
	v_pk_fma_f32 v[80:81], v[80:81], 0.5, v[130:131] op_sel_hi:[1,0,1]
	v_pk_fma_f32 v[82:83], v[82:83], 0.5, v[132:133] op_sel_hi:[1,0,1]
	v_pk_mul_f32 v[130:131], v[134:135], s[22:23] op_sel_hi:[1,0]
	v_pk_mul_f32 v[132:133], v[136:137], s[22:23] op_sel_hi:[1,0]
	v_pk_fma_f32 v[84:85], v[84:85], 0.5, v[130:131] op_sel_hi:[1,0,1]
	v_pk_fma_f32 v[86:87], v[86:87], 0.5, v[132:133] op_sel_hi:[1,0,1]
	v_lshlrev_b32_e32 v130, 16, v192
	v_and_b32_e32 v131, 0xffff0000, v192
	v_lshlrev_b32_e32 v132, 16, v193
	v_and_b32_e32 v133, 0xffff0000, v193
	v_lshlrev_b32_e32 v134, 16, v194
	v_and_b32_e32 v135, 0xffff0000, v194
	v_lshlrev_b32_e32 v136, 16, v195
	v_and_b32_e32 v137, 0xffff0000, v195
	v_pk_mul_f32 v[130:131], v[130:131], s[22:23] op_sel_hi:[1,0]
	v_pk_mul_f32 v[132:133], v[132:133], s[22:23] op_sel_hi:[1,0]
	v_lshlrev_b32_e32 v146, 16, v138
	v_and_b32_e32 v147, 0xffff0000, v138
	v_lshlrev_b32_e32 v138, 16, v139
	v_and_b32_e32 v139, 0xffff0000, v139
	v_lshlrev_b32_e32 v158, 16, v140
	v_and_b32_e32 v159, 0xffff0000, v140
	v_lshlrev_b32_e32 v140, 16, v141
	v_and_b32_e32 v141, 0xffff0000, v141
	v_pk_fma_f32 v[26:27], v[26:27], 0.5, v[132:133] op_sel_hi:[1,0,1]
	v_pk_fma_f32 v[24:25], v[24:25], 0.5, v[130:131] op_sel_hi:[1,0,1]
	v_pk_mul_f32 v[130:131], v[134:135], s[22:23] op_sel_hi:[1,0]
	v_pk_mul_f32 v[132:133], v[136:137], s[22:23] op_sel_hi:[1,0]
	v_pk_fma_f32 v[14:15], v[138:139], s[22:23], v[174:175] op_sel_hi:[1,0,1]
	v_pk_fma_f32 v[12:13], v[146:147], s[22:23], v[196:197] op_sel_hi:[1,0,1]
	v_pk_fma_f32 v[2:3], v[140:141], s[22:23], v[198:199] op_sel_hi:[1,0,1]
	v_pk_fma_f32 v[0:1], v[158:159], s[22:23], v[200:201] op_sel_hi:[1,0,1]
	v_pk_fma_f32 v[30:31], v[30:31], 0.5, v[132:133] op_sel_hi:[1,0,1]
	v_pk_fma_f32 v[28:29], v[28:29], 0.5, v[130:131] op_sel_hi:[1,0,1]
	v_add_co_u32_e32 v142, vcc, s73, v128
	s_nop 1
	v_addc_co_u32_e32 v143, vcc, 0, v129, vcc
	v_add_co_u32_e32 v144, vcc, s74, v128
	v_pk_add_f32 v[174:175], v[54:55], v[50:51]
	s_nop 0
	v_addc_co_u32_e32 v145, vcc, 0, v129, vcc
	v_add_co_u32_e32 v138, vcc, s56, v128
	s_nop 1
	v_addc_co_u32_e32 v139, vcc, 0, v129, vcc
	v_add_co_u32_e32 v128, vcc, s72, v128
	s_nop 1
	v_addc_co_u32_e32 v129, vcc, 0, v129, vcc
	s_nop 0
	v_cmp_eq_u32_e32 vcc, 0, v176
	s_waitcnt vmcnt(7)
	v_lshlrev_b32_e32 v128, 16, v222
	v_and_b32_e32 v129, 0xffff0000, v222
	v_lshlrev_b32_e32 v142, 16, v224
	v_and_b32_e32 v143, 0xffff0000, v224
	v_pk_mul_f32 v[128:129], v[128:129], s[22:23] op_sel_hi:[1,0]
	v_lshlrev_b32_e32 v130, 16, v223
	v_and_b32_e32 v131, 0xffff0000, v223
	v_pk_fma_f32 v[104:105], v[104:105], 0.5, v[128:129] op_sel_hi:[1,0,1]
	v_pk_mul_f32 v[128:129], v[142:143], s[22:23] op_sel_hi:[1,0]
	v_lshlrev_b32_e32 v132, 16, v225
	v_and_b32_e32 v133, 0xffff0000, v225
	v_pk_mul_f32 v[130:131], v[130:131], s[22:23] op_sel_hi:[1,0]
	v_pk_fma_f32 v[108:109], v[108:109], 0.5, v[128:129] op_sel_hi:[1,0,1]
	s_waitcnt vmcnt(6)
	v_lshlrev_b32_e32 v128, 16, v226
	v_and_b32_e32 v129, 0xffff0000, v226
	v_pk_fma_f32 v[106:107], v[106:107], 0.5, v[130:131] op_sel_hi:[1,0,1]
	v_pk_mul_f32 v[130:131], v[132:133], s[22:23] op_sel_hi:[1,0]
	v_lshlrev_b32_e32 v132, 16, v228
	v_and_b32_e32 v133, 0xffff0000, v228
	v_pk_mul_f32 v[128:129], v[128:129], s[22:23] op_sel_hi:[1,0]
	v_pk_fma_f32 v[110:111], v[110:111], 0.5, v[130:131] op_sel_hi:[1,0,1]
	v_lshlrev_b32_e32 v130, 16, v227
	v_and_b32_e32 v131, 0xffff0000, v227
	v_pk_fma_f32 v[32:33], v[32:33], 0.5, v[128:129] op_sel_hi:[1,0,1]
	v_pk_mul_f32 v[128:129], v[132:133], s[22:23] op_sel_hi:[1,0]
	v_lshlrev_b32_e32 v134, 16, v229
	v_and_b32_e32 v135, 0xffff0000, v229
	v_pk_mul_f32 v[130:131], v[130:131], s[22:23] op_sel_hi:[1,0]
	v_pk_fma_f32 v[36:37], v[36:37], 0.5, v[128:129] op_sel_hi:[1,0,1]
	s_waitcnt vmcnt(5)
	v_lshlrev_b32_e32 v128, 16, v230
	v_and_b32_e32 v129, 0xffff0000, v230
	v_pk_fma_f32 v[34:35], v[34:35], 0.5, v[130:131] op_sel_hi:[1,0,1]
	v_pk_mul_f32 v[130:131], v[134:135], s[22:23] op_sel_hi:[1,0]
	v_lshlrev_b32_e32 v132, 16, v232
	v_and_b32_e32 v133, 0xffff0000, v232
	v_pk_mul_f32 v[128:129], v[128:129], s[22:23] op_sel_hi:[1,0]
	v_pk_fma_f32 v[38:39], v[38:39], 0.5, v[130:131] op_sel_hi:[1,0,1]
	v_lshlrev_b32_e32 v130, 16, v231
	v_and_b32_e32 v131, 0xffff0000, v231
	v_pk_fma_f32 v[120:121], v[120:121], 0.5, v[128:129] op_sel_hi:[1,0,1]
	v_pk_mul_f32 v[128:129], v[132:133], s[22:23] op_sel_hi:[1,0]
	v_lshlrev_b32_e32 v134, 16, v233
	v_and_b32_e32 v135, 0xffff0000, v233
	v_pk_mul_f32 v[130:131], v[130:131], s[22:23] op_sel_hi:[1,0]
	v_pk_fma_f32 v[124:125], v[124:125], 0.5, v[128:129] op_sel_hi:[1,0,1]
	s_waitcnt vmcnt(4)
	v_lshlrev_b32_e32 v128, 16, v234
	v_and_b32_e32 v129, 0xffff0000, v234
	v_pk_fma_f32 v[122:123], v[122:123], 0.5, v[130:131] op_sel_hi:[1,0,1]
	v_pk_mul_f32 v[130:131], v[134:135], s[22:23] op_sel_hi:[1,0]
	v_lshlrev_b32_e32 v132, 16, v236
	v_and_b32_e32 v133, 0xffff0000, v236
	v_pk_mul_f32 v[128:129], v[128:129], s[22:23] op_sel_hi:[1,0]
	v_pk_fma_f32 v[126:127], v[126:127], 0.5, v[130:131] op_sel_hi:[1,0,1]
	v_lshlrev_b32_e32 v130, 16, v235
	v_and_b32_e32 v131, 0xffff0000, v235
	v_pk_fma_f32 v[56:57], v[56:57], 0.5, v[128:129] op_sel_hi:[1,0,1]
	v_pk_mul_f32 v[128:129], v[132:133], s[22:23] op_sel_hi:[1,0]
	v_lshlrev_b32_e32 v134, 16, v237
	v_and_b32_e32 v135, 0xffff0000, v237
	v_pk_mul_f32 v[130:131], v[130:131], s[22:23] op_sel_hi:[1,0]
	v_pk_fma_f32 v[60:61], v[60:61], 0.5, v[128:129] op_sel_hi:[1,0,1]
	s_waitcnt vmcnt(3)
	v_lshlrev_b32_e32 v128, 16, v238
	v_and_b32_e32 v129, 0xffff0000, v238
	v_pk_fma_f32 v[58:59], v[58:59], 0.5, v[130:131] op_sel_hi:[1,0,1]
	v_pk_mul_f32 v[130:131], v[134:135], s[22:23] op_sel_hi:[1,0]
	v_lshlrev_b32_e32 v132, 16, v240
	v_and_b32_e32 v133, 0xffff0000, v240
	v_pk_mul_f32 v[128:129], v[128:129], s[22:23] op_sel_hi:[1,0]
	v_pk_fma_f32 v[62:63], v[62:63], 0.5, v[130:131] op_sel_hi:[1,0,1]
	v_lshlrev_b32_e32 v130, 16, v239
	v_and_b32_e32 v131, 0xffff0000, v239
	v_pk_fma_f32 v[128:129], v[116:117], 0.5, v[128:129] op_sel_hi:[1,0,1]
	v_pk_mul_f32 v[116:117], v[132:133], s[22:23] op_sel_hi:[1,0]
	v_lshlrev_b32_e32 v134, 16, v241
	v_and_b32_e32 v135, 0xffff0000, v241
	v_pk_mul_f32 v[130:131], v[130:131], s[22:23] op_sel_hi:[1,0]
	v_pk_fma_f32 v[132:133], v[112:113], 0.5, v[116:117] op_sel_hi:[1,0,1]
	s_waitcnt vmcnt(1)
	v_lshlrev_b32_e32 v112, 16, v246
	v_and_b32_e32 v113, 0xffff0000, v246
	v_pk_fma_f32 v[130:131], v[118:119], 0.5, v[130:131] op_sel_hi:[1,0,1]
	v_pk_mul_f32 v[118:119], v[134:135], s[22:23] op_sel_hi:[1,0]
	v_lshlrev_b32_e32 v116, 16, v248
	v_and_b32_e32 v117, 0xffff0000, v248
	v_pk_mul_f32 v[112:113], v[112:113], s[22:23] op_sel_hi:[1,0]
	v_pk_fma_f32 v[134:135], v[114:115], 0.5, v[118:119] op_sel_hi:[1,0,1]
	v_lshlrev_b32_e32 v114, 16, v247
	v_and_b32_e32 v115, 0xffff0000, v247
	v_pk_fma_f32 v[72:73], v[72:73], 0.5, v[112:113] op_sel_hi:[1,0,1]
	v_pk_mul_f32 v[112:113], v[116:117], s[22:23] op_sel_hi:[1,0]
	v_lshlrev_b32_e32 v118, 16, v249
	v_and_b32_e32 v119, 0xffff0000, v249
	v_pk_mul_f32 v[114:115], v[114:115], s[22:23] op_sel_hi:[1,0]
	v_pk_fma_f32 v[76:77], v[76:77], 0.5, v[112:113] op_sel_hi:[1,0,1]
	v_lshlrev_b32_e32 v112, 16, v242
	v_and_b32_e32 v113, 0xffff0000, v242
	v_pk_fma_f32 v[74:75], v[74:75], 0.5, v[114:115] op_sel_hi:[1,0,1]
	v_pk_mul_f32 v[114:115], v[118:119], s[22:23] op_sel_hi:[1,0]
	v_lshlrev_b32_e32 v116, 16, v244
	v_and_b32_e32 v117, 0xffff0000, v244
	v_pk_mul_f32 v[112:113], v[112:113], s[22:23] op_sel_hi:[1,0]
	v_pk_fma_f32 v[78:79], v[78:79], 0.5, v[114:115] op_sel_hi:[1,0,1]
	v_lshlrev_b32_e32 v114, 16, v243
	v_and_b32_e32 v115, 0xffff0000, v243
	v_pk_fma_f32 v[136:137], v[100:101], 0.5, v[112:113] op_sel_hi:[1,0,1]
	v_pk_mul_f32 v[100:101], v[116:117], s[22:23] op_sel_hi:[1,0]
	v_lshlrev_b32_e32 v118, 16, v245
	v_and_b32_e32 v119, 0xffff0000, v245
	v_pk_mul_f32 v[114:115], v[114:115], s[22:23] op_sel_hi:[1,0]
	v_pk_fma_f32 v[140:141], v[96:97], 0.5, v[100:101] op_sel_hi:[1,0,1]
	s_waitcnt vmcnt(0)
	v_lshlrev_b32_e32 v96, 16, v252
	v_and_b32_e32 v97, 0xffff0000, v252
	v_pk_fma_f32 v[138:139], v[102:103], 0.5, v[114:115] op_sel_hi:[1,0,1]
	v_pk_mul_f32 v[102:103], v[118:119], s[22:23] op_sel_hi:[1,0]
	v_lshlrev_b32_e32 v100, 16, v254
	v_and_b32_e32 v101, 0xffff0000, v254
	v_pk_mul_f32 v[96:97], v[96:97], s[22:23] op_sel_hi:[1,0]
	v_pk_fma_f32 v[142:143], v[98:99], 0.5, v[102:103] op_sel_hi:[1,0,1]
	v_lshlrev_b32_e32 v98, 16, v253
	v_and_b32_e32 v99, 0xffff0000, v253
	v_pk_fma_f32 v[92:93], v[92:93], 0.5, v[96:97] op_sel_hi:[1,0,1]
	v_pk_mul_f32 v[96:97], v[100:101], s[22:23] op_sel_hi:[1,0]
	v_lshlrev_b32_e32 v102, 16, v255
	v_and_b32_e32 v103, 0xffff0000, v255
	v_pk_mul_f32 v[98:99], v[98:99], s[22:23] op_sel_hi:[1,0]
	v_pk_fma_f32 v[88:89], v[88:89], 0.5, v[96:97] op_sel_hi:[1,0,1]
	v_add_u32_e32 v96, s0, v148
	v_pk_fma_f32 v[94:95], v[94:95], 0.5, v[98:99] op_sel_hi:[1,0,1]
	v_pk_mul_f32 v[98:99], v[102:103], s[22:23] op_sel_hi:[1,0]
	v_ashrrev_i32_e32 v97, 31, v96
	v_pk_fma_f32 v[90:91], v[90:91], 0.5, v[98:99] op_sel_hi:[1,0,1]
	v_lshlrev_b64 v[96:97], 2, v[96:97]
	v_lshl_add_u64 v[100:101], s[14:15], 0, v[96:97]
	v_lshl_add_u64 v[116:117], s[16:17], 0, v[96:97]
	global_load_dwordx4 v[144:147], v[100:101], off offset:16
	global_load_dwordx4 v[152:155], v[100:101], off
	global_load_dwordx4 v[148:151], v[116:117], off offset:16
	global_load_dwordx4 v[156:159], v[116:117], off
	global_load_dwordx4 v[96:99], v[100:101], off offset:528
	global_load_dwordx4 v[112:115], v[100:101], off offset:512
	s_nop 0
	global_load_dwordx4 v[100:103], v[116:117], off offset:528
	s_nop 0
	global_load_dwordx4 v[116:119], v[116:117], off offset:512
	v_pk_add_f32 v[178:179], v[52:53], v[48:49]
	v_pk_add_f32 v[180:181], v[14:15], v[2:3]
	v_pk_add_f32 v[192:193], v[12:13], v[0:1]
	v_pk_add_f32 v[174:175], v[174:175], v[180:181]
	v_pk_add_f32 v[178:179], v[178:179], v[192:193]
	v_add_f32_e32 v174, v174, v175
	v_add_f32_e32 v178, v178, v179
	v_add_f32_e32 v174, v178, v174
	v_mov_b32_e32 v175, v174
	s_nop 1
	v_permlane16_swap_b32_e32 v174, v175
	v_add_f32_e32 v174, v174, v175
	v_mov_b32_e32 v175, v174
	s_nop 1
	v_permlane32_swap_b32_e32 v174, v175
	v_add_f32_e32 v174, v174, v175
	v_fmamk_f32 v193, v174, 0xbc800000, v49
	v_fmamk_f32 v192, v174, 0xbc800000, v48
	v_fmamk_f32 v195, v174, 0xbc800000, v51
	v_fmamk_f32 v194, v174, 0xbc800000, v50
	v_fmamk_f32 v179, v174, 0xbc800000, v55
	v_fmamk_f32 v178, v174, 0xbc800000, v54
	v_fmamk_f32 v181, v174, 0xbc800000, v53
	v_fmamk_f32 v180, v174, 0xbc800000, v52
	v_fmamk_f32 v201, v174, 0xbc800000, v1
	v_fmamk_f32 v200, v174, 0xbc800000, v0
	v_fmamk_f32 v203, v174, 0xbc800000, v3
	v_fmamk_f32 v202, v174, 0xbc800000, v2
	v_pk_mul_f32 v[194:195], v[194:195], v[194:195]
	v_pk_mul_f32 v[192:193], v[192:193], v[192:193]
	v_fmamk_f32 v197, v174, 0xbc800000, v15
	v_fmamk_f32 v196, v174, 0xbc800000, v14
	v_fmamk_f32 v199, v174, 0xbc800000, v13
	v_fmamk_f32 v198, v174, 0xbc800000, v12
	v_pk_fma_f32 v[180:181], v[180:181], v[180:181], v[192:193]
	v_pk_fma_f32 v[178:179], v[178:179], v[178:179], v[194:195]
	v_pk_mul_f32 v[192:193], v[202:203], v[202:203]
	v_pk_mul_f32 v[194:195], v[200:201], v[200:201]
	v_pk_fma_f32 v[192:193], v[196:197], v[196:197], v[192:193]
	v_pk_fma_f32 v[194:195], v[198:199], v[198:199], v[194:195]
	v_pk_add_f32 v[178:179], v[178:179], v[192:193]
	v_pk_add_f32 v[180:181], v[180:181], v[194:195]
	v_add_f32_e32 v178, v178, v179
	v_add_f32_e32 v175, v180, v181
	v_add_f32_e32 v175, v175, v178
	v_mov_b32_e32 v178, v175
	s_nop 1
	v_permlane16_swap_b32_e32 v175, v178
	s_lshl_b32 s0, s3, 3
	v_add_f32_e32 v175, v175, v178
	s_add_i32 s5, s0, 0
	v_mov_b32_e32 v178, v175
	s_add_i32 s5, s5, 0x21000
	s_nop 0
	v_permlane32_swap_b32_e32 v175, v178
	s_and_saveexec_b64 s[0:1], vcc
	s_cbranch_execz .LBB0_2971
	s_lshl_b32 s6, s2, 11
	s_add_i32 s6, s5, s6
	v_mul_f32_e32 v174, 0x3c800000, v174
	v_lshl_add_u32 v179, v177, 5, s6
	v_add_f32_e32 v175, v175, v178
	ds_write_b64 v179, v[174:175]

	.amdhsa_kernel _Z10hybrid_fwd4Args
		.amdhsa_group_segment_fixed_size 0
		.amdhsa_private_segment_fixed_size 0
		.amdhsa_kernarg_size 440
		.amdhsa_user_sgpr_count 2
		.amdhsa_user_sgpr_dispatch_ptr 0
		.amdhsa_user_sgpr_queue_ptr 0
		.amdhsa_user_sgpr_kernarg_segment_ptr 1
		.amdhsa_user_sgpr_dispatch_id 0
		.amdhsa_user_sgpr_kernarg_preload_length 0
		.amdhsa_user_sgpr_kernarg_preload_offset 0
		.amdhsa_user_sgpr_private_segment_size 0
		.amdhsa_uses_dynamic_stack 0
		.amdhsa_enable_private_segment 0
		.amdhsa_system_sgpr_workgroup_id_x 1
		.amdhsa_system_sgpr_workgroup_id_y 0
		.amdhsa_system_sgpr_workgroup_id_z 0
		.amdhsa_system_sgpr_workgroup_info 0
		.amdhsa_system_vgpr_workitem_id 0
		.amdhsa_next_free_vgpr 256
		.amdhsa_next_free_sgpr 102
		.amdhsa_accum_offset 256
		.amdhsa_reserve_vcc 1
		.amdhsa_float_round_mode_32 0
		.amdhsa_float_round_mode_16_64 0
		.amdhsa_float_denorm_mode_32 3
		.amdhsa_float_denorm_mode_16_64 3
		.amdhsa_dx10_clamp 1
		.amdhsa_ieee_mode 1
		.amdhsa_fp16_overflow 0
		.amdhsa_tg_split 0
		.amdhsa_exception_fp_ieee_invalid_op 0
		.amdhsa_exception_fp_denorm_src 0
		.amdhsa_exception_fp_ieee_div_zero 0
		.amdhsa_exception_fp_ieee_overflow 0
		.amdhsa_exception_fp_ieee_underflow 0
		.amdhsa_exception_fp_ieee_inexact 0
		.amdhsa_exception_int_div_zero 0
	.end_amdhsa_kernel

amdhsa.kernels:
  - .agpr_count:     0
    .args:
      - .offset:         0
        .size:           184
        .value_kind:     by_value
      - .offset:         184
        .size:           4
        .value_kind:     hidden_block_count_x
      - .offset:         188
        .size:           4
        .value_kind:     hidden_block_count_y
      - .offset:         192
        .size:           4
        .value_kind:     hidden_block_count_z
      - .offset:         196
        .size:           2
        .value_kind:     hidden_group_size_x
      - .offset:         198
        .size:           2
        .value_kind:     hidden_group_size_y
      - .offset:         200
        .size:           2
        .value_kind:     hidden_group_size_z
      - .offset:         202
        .size:           2
        .value_kind:     hidden_remainder_x
      - .offset:         204
        .size:           2
        .value_kind:     hidden_remainder_y
      - .offset:         206
        .size:           2
        .value_kind:     hidden_remainder_z
      - .offset:         224
        .size:           8
        .value_kind:     hidden_global_offset_x
      - .offset:         232
        .size:           8
        .value_kind:     hidden_global_offset_y
      - .offset:         240
        .size:           8
        .value_kind:     hidden_global_offset_z
      - .offset:         248
        .size:           2
        .value_kind:     hidden_grid_dims
      - .offset:         304
        .size:           4
        .value_kind:     hidden_dynamic_lds_size
    .group_segment_fixed_size: 0
    .kernarg_segment_align: 8
    .kernarg_segment_size: 440
    .language:       OpenCL C
    .language_version:
      - 2
      - 0
    .max_flat_workgroup_size: 512
    .name:           _Z10hybrid_fwd4Args
    .private_segment_fixed_size: 0
    .sgpr_count:     108
    .sgpr_spill_count: 34
    .symbol:         _Z10hybrid_fwd4Args.kd
    .uniform_work_group_size: 1
    .uses_dynamic_stack: false
    .vgpr_count:     256
    .vgpr_spill_count: 0
    .wavefront_size: 64
